# latent rows: out-proj epilogue reads the residual from its source (x / x_new) and stores, so the norm phases no longer copy latent rows into x_new / out
# speedup vs baseline: 1.0456x; 1.0063x over previous
; __device__ __forceinline__ unsigned pack2(float a, float b) { return (unsigned)f2bf(a) | ((unsigned)f2bf(b) << 16); }
; __device__ __forceinline__ void norm_job(const Params& p, int l, int job, bool from_x) {
;     ...
;     int row = rowbase0 + i;
;     int v = row < MLAT ? (row >> 13) : 2;
;     const float* mods = (const float*)(ws + OFF_MODS) + (l * 3 + v) * 6144;
;     float4 xv[4];
;     xv[0] = nx0; xv[1] = nx1; xv[2] = nx2; xv[3] = nx3;
;     if (i + 1 < 16) {
;       const float* sn = src0 + (size_t)(i + 1) * 1024;
;       nx0 = *(const float4*)&sn[lane * 4]; nx1 = *(const float4*)&sn[lane * 4 + 256];
;       nx2 = *(const float4*)&sn[lane * 4 + 512]; nx3 = *(const float4*)&sn[lane * 4 + 768];
;     }
;     float ss = 0.f;
; #pragma unroll
;     for (int q = 0; q < 4; ++q) {
;       ss += xv[q].x * xv[q].x + xv[q].y * xv[q].y + xv[q].z * xv[q].z + xv[q].w * xv[q].w;
;     }
;     ss = wave_sum(ss);
;     float rstd = rsqrtf(ss * (1.f / 1024.f) + EPSF);
;     if (from_x) {
;       float* dstr = (float*)(ws + OFF_XNEW) + (size_t)row * 1024;
; #pragma unroll
;       for (int q = 0; q < 4; ++q) *(float4*)&dstr[lane * 4 + 256 * q] = xv[q];
;     } else if (row < MLAT) {
;       float* dstr = p.out + (size_t)row * 1024;
; #pragma unroll
;       for (int q = 0; q < 4; ++q) *(float4*)&dstr[lane * 4 + 256 * q] = xv[q];
;     }
; #pragma unroll
;     for (int q = 0; q < 4; ++q) {
;       int col = lane * 4 + 256 * q;
;       float4 w = *(const float4*)&nw[col];
;       float4 sh = *(const float4*)&mods[col];
;       float4 sc = *(const float4*)&mods[1024 + col];
;       float o0 = xv[q].x * rstd * w.x * (1.f + sc.x) + sh.x;
;       float o1 = xv[q].y * rstd * w.y * (1.f + sc.y) + sh.y;
;       float o2 = xv[q].z * rstd * w.z * (1.f + sc.z) + sh.z;
;       float o3 = xv[q].w * rstd * w.w * (1.f + sc.w) + sh.w;
;       uint2 o; o.x = pack2(o0, o1); o.y = pack2(o2, o3);
;       *(uint2*)&HL[(size_t)row * 1024 + col] = o;
.LBB0_171:
	s_waitcnt vmcnt(0)
	v_mov_b64_e32 v[22:23], v[2:3]
	v_mov_b64_e32 v[26:27], v[10:11]
	v_mov_b64_e32 v[54:55], v[14:15]
	v_cmp_gt_i32_e32 vcc, s84, v40
	v_mov_b64_e32 v[20:21], v[0:1]
	v_mov_b64_e32 v[24:25], v[8:9]
	v_mov_b64_e32 v[52:53], v[12:13]
	v_lshl_add_u64 v[0:1], v[32:33], 0, s[54:55]
	v_cndmask_b32_e32 v7, 2, v49, vcc
	v_ashrrev_i32_e32 v41, 31, v40
	v_add_co_u32_e32 v6, vcc, 0x1000, v0
	v_mov_b32_e32 v10, v53
	v_mov_b32_e32 v11, v25
	v_add_u32_e32 v0, s48, v7
	v_mov_b32_e32 v5, v17
	v_mov_b32_e32 v8, v52
	v_mov_b32_e32 v9, v24
	v_mov_b32_e32 v4, v21
	v_lshlrev_b64 v[12:13], 12, v[40:41]
	v_pk_mul_f32 v[10:11], v[10:11], v[10:11]
	v_mul_lo_u32 v76, v0, s88
	v_mov_b32_e32 v3, v16
	v_mov_b32_e32 v58, v54
	v_mov_b32_e32 v59, v26
	v_mov_b32_e32 v2, v20
	v_lshlrev_b64 v[14:15], 11, v[40:41]
	v_pk_mul_f32 v[4:5], v[4:5], v[4:5]
	v_lshl_add_u64 v[74:75], v[34:35], 0, v[12:13]
	v_addc_co_u32_e32 v7, vcc, 0, v1, vcc
	v_pk_fma_f32 v[78:79], v[8:9], v[8:9], v[10:11]
	v_ashrrev_i32_e32 v77, 31, v76
	v_mov_b32_e32 v68, v52
	v_mov_b32_e32 v69, v54
	v_lshl_add_u64 v[42:43], v[38:39], 0, v[14:15]
	v_pk_fma_f32 v[80:81], v[2:3], v[2:3], v[4:5]
	global_load_dwordx4 v[12:15], v[6:7], off
	global_load_dwordx4 v[8:11], v[6:7], off offset:1024
	global_load_dwordx4 v[0:3], v[6:7], off offset:2048
	s_nop 0
	global_load_dwordx4 v[4:7], v[6:7], off offset:3072
	s_nop 0
	v_cmp_le_i32_e64 s[100:101], s84, v40
	s_and_saveexec_b64 s[100:101], s[100:101]
	global_store_dwordx4 v[74:75], v[52:55], off
	global_store_dwordx4 v[74:75], v[24:27], off offset:1024
	global_store_dwordx4 v[74:75], v[20:23], off offset:2048
	global_store_dwordx4 v[74:75], v[16:19], off offset:3072
	s_or_b64 exec, exec, s[100:101]
	v_mov_b32_e32 v54, v53
	v_pk_fma_f32 v[52:53], v[58:59], v[58:59], v[78:79]
	v_lshl_add_u64 v[78:79], v[76:77], 2, v[36:37]
	v_mov_b32_e32 v57, v18
	v_mov_b32_e32 v56, v22
	v_add_co_u32_e32 v82, vcc, s83, v78
	v_mov_b32_e32 v61, v19
	v_mov_b32_e32 v62, v55
	v_mov_b32_e32 v63, v27
	v_mov_b32_e32 v60, v23
	v_pk_fma_f32 v[74:75], v[56:57], v[56:57], v[80:81]
	v_mov_b64_e32 v[56:57], v[186:187]
	v_mov_b64_e32 v[58:59], v[188:189]
	v_addc_co_u32_e32 v83, vcc, 0, v79, vcc
	v_pk_fma_f32 v[52:53], v[62:63], v[62:63], v[52:53]
	v_pk_fma_f32 v[80:81], v[60:61], v[60:61], v[74:75]
	v_mov_b64_e32 v[60:61], v[190:191]
	v_mov_b64_e32 v[62:63], v[192:193]
	v_mov_b64_e32 v[74:75], v[194:195]
	v_mov_b64_e32 v[76:77], v[196:197]
	v_add_f32_e32 v41, v52, v53
	v_add_f32_e32 v41, v41, v80
	v_add_f32_e32 v41, v41, v81
	ds_bpermute_b32 v51, v31, v41
	s_add_u32 s54, s54, 0x1000
	s_addc_u32 s55, s55, 0
	v_add_u32_e32 v40, 1, v40
	s_cmpk_lg_u32 s54, 0xf000
	s_waitcnt lgkmcnt(0)
	v_add_f32_e32 v41, v41, v51
	ds_bpermute_b32 v51, v44, v41
	s_waitcnt lgkmcnt(0)
	v_add_f32_e32 v41, v41, v51
	ds_bpermute_b32 v51, v45, v41
	s_waitcnt lgkmcnt(0)
	v_add_f32_e32 v41, v41, v51
	ds_bpermute_b32 v51, v46, v41
	s_waitcnt lgkmcnt(0)
	v_add_f32_e32 v41, v41, v51
	ds_bpermute_b32 v51, v47, v41
	s_waitcnt lgkmcnt(0)
	v_add_f32_e32 v41, v41, v51
	ds_bpermute_b32 v51, v48, v41
	s_waitcnt lgkmcnt(0)
	v_add_f32_e32 v41, v41, v51
	v_fmamk_f32 v41, v41, 0x3a800000, v70
	v_mul_f32_e32 v51, 0x4b800000, v41
	v_cmp_gt_f32_e32 vcc, s89, v41
	s_nop 1
	v_cndmask_b32_e32 v41, v41, v51, vcc
	v_rsq_f32_e32 v41, v41
	s_nop 0
	v_mul_f32_e32 v51, 0x45800000, v41
	v_cndmask_b32_e32 v64, v41, v51, vcc
	v_pk_mul_f32 v[52:53], v[68:69], v[64:65] op_sel_hi:[1,0]
	v_pk_mul_f32 v[54:55], v[54:55], v[64:65] op_sel_hi:[1,0]
	s_waitcnt vmcnt(0)
	v_mov_b32_e32 v69, v58
	v_mov_b32_e32 v58, v57
	v_mov_b32_e32 v68, v56
	v_pk_mul_f32 v[54:55], v[58:59], v[54:55]
	v_pk_mul_f32 v[52:53], v[68:69], v[52:53]
	v_mov_b32_e32 v56, v60
	v_mov_b32_e32 v58, v74
	v_mov_b32_e32 v59, v76
	v_mov_b32_e32 v76, v75
	v_mov_b32_e32 v57, v62
	v_mov_b32_e32 v62, v61
	v_pk_add_f32 v[58:59], v[58:59], 1.0 op_sel_hi:[1,0]
	v_pk_add_f32 v[60:61], v[76:77], 1.0 op_sel_hi:[1,0]
	v_pk_fma_f32 v[52:53], v[52:53], v[58:59], v[56:57]
	v_pk_fma_f32 v[54:55], v[54:55], v[60:61], v[62:63]
	v_and_b32_sdwa v41, v53, v73 dst_sel:DWORD dst_unused:UNUSED_PAD src0_sel:WORD_1 src1_sel:DWORD
	v_and_b32_sdwa v51, v52, v73 dst_sel:DWORD dst_unused:UNUSED_PAD src0_sel:WORD_1 src1_sel:DWORD
	v_and_b32_sdwa v56, v55, v73 dst_sel:DWORD dst_unused:UNUSED_PAD src0_sel:WORD_1 src1_sel:DWORD
	v_and_b32_sdwa v57, v54, v73 dst_sel:DWORD dst_unused:UNUSED_PAD src0_sel:WORD_1 src1_sel:DWORD
	v_add3_u32 v51, v52, v51, s87
	v_add3_u32 v41, v53, v41, s87
	v_add3_u32 v52, v55, v56, s87
	v_add3_u32 v53, v54, v57, s87
	v_and_b32_e32 v52, 0xffff0000, v52
	v_and_b32_e32 v54, 0xffff0000, v53
	v_or_b32_sdwa v53, v52, v41 dst_sel:DWORD dst_unused:UNUSED_PAD src0_sel:DWORD src1_sel:WORD_1
	v_or_b32_sdwa v52, v54, v51 dst_sel:DWORD dst_unused:UNUSED_PAD src0_sel:DWORD src1_sel:WORD_1
	global_store_dwordx2 v[42:43], v[52:53], off
	v_mov_b64_e32 v[52:53], v[198:199]
	v_mov_b64_e32 v[54:55], v[200:201]
	s_nop 0
	v_mov_b64_e32 v[56:57], v[206:207]
	v_mov_b64_e32 v[58:59], v[208:209]
	v_mov_b64_e32 v[60:61], v[202:203]
	v_mov_b64_e32 v[62:63], v[204:205]
	v_mov_b32_e32 v68, v24
	v_mov_b32_e32 v69, v26
	v_mov_b32_e32 v26, v25
	v_pk_mul_f32 v[24:25], v[68:69], v[64:65] op_sel_hi:[1,0]
	v_pk_mul_f32 v[26:27], v[26:27], v[64:65] op_sel_hi:[1,0]
	v_mov_b32_e32 v69, v54
	s_waitcnt lgkmcnt(0)
; __device__ __forceinline__ unsigned pack2(float a, float b) { return (unsigned)f2bf(a) | ((unsigned)f2bf(b) << 16); }
; __device__ __forceinline__ void norm_job(const Params& p, int l, int job, bool from_x) {
;     ...
; #pragma unroll
;     for (int q = 0; q < 4; ++q) {
;       int col = lane * 4 + 256 * q;
;       float4 w = *(const float4*)&nw[col];
;       float4 sh = *(const float4*)&mods[col];
;       float4 sc = *(const float4*)&mods[1024 + col];
;       float o0 = xv[q].x * rstd * w.x * (1.f + sc.x) + sh.x;
;       float o1 = xv[q].y * rstd * w.y * (1.f + sc.y) + sh.y;
;       float o2 = xv[q].z * rstd * w.z * (1.f + sc.z) + sh.z;
;       float o3 = xv[q].w * rstd * w.w * (1.f + sc.w) + sh.w;
;       uint2 o; o.x = pack2(o0, o1); o.y = pack2(o2, o3);
;       *(uint2*)&HL[(size_t)row * 1024 + col] = o;
;     }
	v_mov_b32_e32 v75, v58
	v_mov_b32_e32 v54, v53
	v_mov_b32_e32 v58, v57
	v_mov_b32_e32 v68, v52
	v_mov_b32_e32 v74, v56
	v_mov_b32_e32 v77, v62
	v_mov_b32_e32 v62, v61
	v_pk_mul_f32 v[26:27], v[26:27], v[54:55]
	v_pk_add_f32 v[54:55], v[58:59], 1.0 op_sel_hi:[1,0]
	v_mov_b32_e32 v76, v60
	v_pk_mul_f32 v[24:25], v[24:25], v[68:69]
	v_pk_add_f32 v[52:53], v[74:75], 1.0 op_sel_hi:[1,0]
	v_pk_fma_f32 v[26:27], v[26:27], v[54:55], v[62:63]
	v_pk_fma_f32 v[24:25], v[24:25], v[52:53], v[76:77]
	v_and_b32_sdwa v52, v27, v73 dst_sel:DWORD dst_unused:UNUSED_PAD src0_sel:WORD_1 src1_sel:DWORD
	v_and_b32_sdwa v53, v26, v73 dst_sel:DWORD dst_unused:UNUSED_PAD src0_sel:WORD_1 src1_sel:DWORD
	v_and_b32_sdwa v41, v25, v73 dst_sel:DWORD dst_unused:UNUSED_PAD src0_sel:WORD_1 src1_sel:DWORD
	v_and_b32_sdwa v51, v24, v73 dst_sel:DWORD dst_unused:UNUSED_PAD src0_sel:WORD_1 src1_sel:DWORD
	v_add3_u32 v27, v27, v52, s87
	v_add3_u32 v26, v26, v53, s87
	v_add3_u32 v24, v24, v51, s87
	v_add3_u32 v25, v25, v41, s87
	v_and_b32_e32 v27, 0xffff0000, v27
	v_and_b32_e32 v26, 0xffff0000, v26
	v_or_b32_sdwa v25, v27, v25 dst_sel:DWORD dst_unused:UNUSED_PAD src0_sel:DWORD src1_sel:WORD_1
	v_or_b32_sdwa v24, v26, v24 dst_sel:DWORD dst_unused:UNUSED_PAD src0_sel:DWORD src1_sel:WORD_1
	global_store_dwordx2 v[42:43], v[24:25], off offset:512
	v_mov_b64_e32 v[24:25], v[210:211]
	v_mov_b64_e32 v[26:27], v[212:213]
	s_nop 0
	v_mov_b64_e32 v[52:53], v[218:219]
	v_mov_b64_e32 v[54:55], v[220:221]
	v_mov_b64_e32 v[56:57], v[214:215]
	v_mov_b64_e32 v[58:59], v[216:217]
	v_mov_b32_e32 v60, v20
	v_mov_b32_e32 v61, v22
	v_mov_b32_e32 v22, v21
	v_pk_mul_f32 v[20:21], v[60:61], v[64:65] op_sel_hi:[1,0]
	v_pk_mul_f32 v[22:23], v[22:23], v[64:65] op_sel_hi:[1,0]
	v_mov_b32_e32 v61, v26
	s_waitcnt lgkmcnt(0)
	v_mov_b32_e32 v63, v54
	v_mov_b32_e32 v26, v25
	v_mov_b32_e32 v54, v53
	v_mov_b32_e32 v60, v24
	v_mov_b32_e32 v62, v52
	v_mov_b32_e32 v69, v58
	v_mov_b32_e32 v58, v57
	v_pk_mul_f32 v[22:23], v[22:23], v[26:27]
	v_pk_add_f32 v[26:27], v[54:55], 1.0 op_sel_hi:[1,0]
	v_mov_b32_e32 v68, v56
	v_pk_mul_f32 v[20:21], v[20:21], v[60:61]
	v_pk_add_f32 v[24:25], v[62:63], 1.0 op_sel_hi:[1,0]
	v_pk_fma_f32 v[22:23], v[22:23], v[26:27], v[58:59]
	v_pk_fma_f32 v[20:21], v[20:21], v[24:25], v[68:69]
	v_and_b32_sdwa v26, v23, v73 dst_sel:DWORD dst_unused:UNUSED_PAD src0_sel:WORD_1 src1_sel:DWORD
	v_and_b32_sdwa v27, v22, v73 dst_sel:DWORD dst_unused:UNUSED_PAD src0_sel:WORD_1 src1_sel:DWORD
	v_and_b32_sdwa v24, v21, v73 dst_sel:DWORD dst_unused:UNUSED_PAD src0_sel:WORD_1 src1_sel:DWORD
	v_and_b32_sdwa v25, v20, v73 dst_sel:DWORD dst_unused:UNUSED_PAD src0_sel:WORD_1 src1_sel:DWORD
	v_add3_u32 v23, v23, v26, s87
	v_add3_u32 v22, v22, v27, s87
	v_add3_u32 v20, v20, v25, s87
	v_add3_u32 v21, v21, v24, s87
	v_and_b32_e32 v23, 0xffff0000, v23
	v_and_b32_e32 v22, 0xffff0000, v22
	v_or_b32_sdwa v21, v23, v21 dst_sel:DWORD dst_unused:UNUSED_PAD src0_sel:DWORD src1_sel:WORD_1
	v_or_b32_sdwa v20, v22, v20 dst_sel:DWORD dst_unused:UNUSED_PAD src0_sel:DWORD src1_sel:WORD_1
	global_store_dwordx2 v[42:43], v[20:21], off offset:1024
	v_mov_b64_e32 v[20:21], v[222:223]
	v_mov_b64_e32 v[22:23], v[224:225]
	s_nop 0
	v_mov_b64_e32 v[24:25], v[230:231]
	v_mov_b64_e32 v[26:27], v[232:233]
	v_mov_b64_e32 v[52:53], v[226:227]
	v_mov_b64_e32 v[54:55], v[228:229]
	v_mov_b32_e32 v57, v18
	v_mov_b32_e32 v18, v17
	v_mov_b32_e32 v56, v16
	v_pk_mul_f32 v[58:59], v[18:19], v[64:65] op_sel_hi:[1,0]
	v_pk_mul_f32 v[56:57], v[56:57], v[64:65] op_sel_hi:[1,0]
	v_mov_b64_e32 v[18:19], v[6:7]
	v_mov_b64_e32 v[16:17], v[4:5]
	v_mov_b32_e32 v61, v22
	s_waitcnt lgkmcnt(0)
	v_mov_b32_e32 v63, v26
	v_mov_b32_e32 v22, v21
	v_mov_b32_e32 v26, v25
	v_mov_b32_e32 v60, v20
	v_mov_b32_e32 v62, v24
	v_mov_b32_e32 v69, v54
	v_mov_b32_e32 v54, v53
	v_pk_mul_f32 v[22:23], v[58:59], v[22:23]
	v_pk_add_f32 v[26:27], v[26:27], 1.0 op_sel_hi:[1,0]
	v_mov_b32_e32 v68, v52
	v_pk_mul_f32 v[20:21], v[56:57], v[60:61]
	v_pk_add_f32 v[24:25], v[62:63], 1.0 op_sel_hi:[1,0]
	v_pk_fma_f32 v[22:23], v[22:23], v[26:27], v[54:55]
	v_pk_fma_f32 v[20:21], v[20:21], v[24:25], v[68:69]
	v_and_b32_sdwa v26, v23, v73 dst_sel:DWORD dst_unused:UNUSED_PAD src0_sel:WORD_1 src1_sel:DWORD
	v_and_b32_sdwa v27, v22, v73 dst_sel:DWORD dst_unused:UNUSED_PAD src0_sel:WORD_1 src1_sel:DWORD
	v_and_b32_sdwa v24, v21, v73 dst_sel:DWORD dst_unused:UNUSED_PAD src0_sel:WORD_1 src1_sel:DWORD
	v_and_b32_sdwa v25, v20, v73 dst_sel:DWORD dst_unused:UNUSED_PAD src0_sel:WORD_1 src1_sel:DWORD
	v_add3_u32 v23, v23, v26, s87
	v_add3_u32 v22, v22, v27, s87
	v_add3_u32 v20, v20, v25, s87
	v_add3_u32 v21, v21, v24, s87
	v_and_b32_e32 v23, 0xffff0000, v23
	v_and_b32_e32 v22, 0xffff0000, v22
	v_or_b32_sdwa v21, v23, v21 dst_sel:DWORD dst_unused:UNUSED_PAD src0_sel:DWORD src1_sel:WORD_1
	v_or_b32_sdwa v20, v22, v20 dst_sel:DWORD dst_unused:UNUSED_PAD src0_sel:DWORD src1_sel:WORD_1
	global_store_dwordx2 v[42:43], v[20:21], off offset:1536
	s_cbranch_scc1 .LBB0_171
; __device__ __forceinline__ unsigned pack2(float a, float b) { return (unsigned)f2bf(a) | ((unsigned)f2bf(b) << 16); }
; __device__ __forceinline__ void norm_job(const Params& p, int l, int job, bool from_x) {
;     ...
;   for (int i = 0; i < 16; ++i) {
;     int row = rowbase0 + i;
;     int v = row < MLAT ? (row >> 13) : 2;
;     const float* mods = (const float*)(ws + OFF_MODS) + (l * 3 + v) * 6144;
;     float4 xv[4];
;     xv[0] = nx0; xv[1] = nx1; xv[2] = nx2; xv[3] = nx3;
;     if (i + 1 < 16) {
;       const float* sn = src0 + (size_t)(i + 1) * 1024;
;       nx0 = *(const float4*)&sn[lane * 4]; nx1 = *(const float4*)&sn[lane * 4 + 256];
;       nx2 = *(const float4*)&sn[lane * 4 + 512]; nx3 = *(const float4*)&sn[lane * 4 + 768];
;     }
;     float ss = 0.f;
; #pragma unroll
;     for (int q = 0; q < 4; ++q) {
;       ss += xv[q].x * xv[q].x + xv[q].y * xv[q].y + xv[q].z * xv[q].z + xv[q].w * xv[q].w;
;     }
;     ss = wave_sum(ss);
;     float rstd = rsqrtf(ss * (1.f / 1024.f) + EPSF);
;     if (from_x) {
;       float* dstr = (float*)(ws + OFF_XNEW) + (size_t)row * 1024;
; #pragma unroll
;       for (int q = 0; q < 4; ++q) *(float4*)&dstr[lane * 4 + 256 * q] = xv[q];
;     } else if (row < MLAT) {
;       float* dstr = p.out + (size_t)row * 1024;
; #pragma unroll
;       for (int q = 0; q < 4; ++q) *(float4*)&dstr[lane * 4 + 256 * q] = xv[q];
;     }
; #pragma unroll
;     for (int q = 0; q < 4; ++q) {
;       int col = lane * 4 + 256 * q;
;       float4 w = *(const float4*)&nw[col];
;       float4 sh = *(const float4*)&mods[col];
;       float4 sc = *(const float4*)&mods[1024 + col];
;       float o0 = xv[q].x * rstd * w.x * (1.f + sc.x) + sh.x;
;       float o1 = xv[q].y * rstd * w.y * (1.f + sc.y) + sh.y;
;       float o2 = xv[q].z * rstd * w.z * (1.f + sc.z) + sh.z;
;       float o3 = xv[q].w * rstd * w.w * (1.f + sc.w) + sh.w;
;       uint2 o; o.x = pack2(o0, o1); o.y = pack2(o2, o3);
;       *(uint2*)&HL[(size_t)row * 1024 + col] = o;
;     }
;   }
	s_waitcnt vmcnt(0)
	v_or_b32_e32 v26, 15, v50
	v_ashrrev_i32_e32 v27, 31, v26
	v_lshlrev_b64 v[16:17], 12, v[26:27]
	v_lshl_add_u64 v[16:17], s[52:53], 0, v[16:17]
	v_lshlrev_b32_e32 v64, 2, v30
	v_lshl_add_u64 v[16:17], v[16:17], 0, v[64:65]
	v_cmp_gt_i32_e32 vcc, s84, v26
	v_cmp_le_i32_e64 s[100:101], s84, v26
	s_and_saveexec_b64 s[100:101], s[100:101]
	global_store_dwordx4 v[16:17], v[12:15], off
	global_store_dwordx4 v[16:17], v[8:11], off offset:1024
	global_store_dwordx4 v[16:17], v[0:3], off offset:2048
	global_store_dwordx4 v[16:17], v[4:7], off offset:3072
	s_or_b64 exec, exec, s[100:101]
	v_cndmask_b32_e32 v16, 2, v49, vcc
	v_add_u32_e32 v16, s48, v16
	v_mul_lo_u32 v16, v16, s88
	v_ashrrev_i32_e32 v17, 31, v16
	v_lshl_add_u64 v[16:17], v[16:17], 2, s[4:5]
	v_lshl_add_u64 v[16:17], v[16:17], 0, v[64:65]
	v_add_co_u32_e32 v40, vcc, s83, v16
	v_mov_b64_e32 v[18:19], v[186:187]
	v_mov_b64_e32 v[20:21], v[188:189]
	s_nop 0
	v_addc_co_u32_e32 v41, vcc, 0, v17, vcc
	v_mov_b64_e32 v[32:33], v[194:195]
	v_mov_b64_e32 v[34:35], v[196:197]
	v_mov_b64_e32 v[22:23], v[190:191]
	v_mov_b64_e32 v[24:25], v[192:193]
	v_mov_b32_e32 v38, v13
	v_mov_b32_e32 v39, v9
	v_mov_b32_e32 v36, v12
	v_mov_b32_e32 v37, v8
	v_pk_mul_f32 v[38:39], v[38:39], v[38:39]
	v_mov_b32_e32 v42, v1
	v_pk_fma_f32 v[36:37], v[36:37], v[36:37], v[38:39]
	v_mov_b32_e32 v38, v14
	v_mov_b32_e32 v39, v10
	v_pk_fma_f32 v[36:37], v[38:39], v[38:39], v[36:37]
	v_mov_b32_e32 v38, v15
	v_mov_b32_e32 v39, v11
	v_mov_b32_e32 v43, v5
	v_pk_fma_f32 v[36:37], v[38:39], v[38:39], v[36:37]
	v_mov_b32_e32 v38, v0
	v_mov_b32_e32 v39, v4
	v_pk_mul_f32 v[42:43], v[42:43], v[42:43]
	v_add_f32_e32 v36, v36, v37
	v_pk_fma_f32 v[38:39], v[38:39], v[38:39], v[42:43]
	v_mov_b32_e32 v42, v2
	v_mov_b32_e32 v43, v6
	v_pk_fma_f32 v[38:39], v[42:43], v[42:43], v[38:39]
	v_mov_b32_e32 v42, v3
	v_mov_b32_e32 v43, v7
	v_pk_fma_f32 v[38:39], v[42:43], v[42:43], v[38:39]
	v_mov_b32_e32 v37, v14
	v_add_f32_e32 v36, v36, v38
	v_add_f32_e32 v36, v36, v39
	ds_bpermute_b32 v31, v31, v36
	v_lshlrev_b32_e32 v64, 1, v30
	v_lshlrev_b64 v[26:27], 11, v[26:27]
	v_lshl_add_u64 v[26:27], s[0:1], 0, v[26:27]
	v_lshl_add_u64 v[26:27], v[26:27], 0, v[64:65]
	s_waitcnt lgkmcnt(0)
	v_add_f32_e32 v31, v36, v31
	ds_bpermute_b32 v36, v44, v31
	s_waitcnt lgkmcnt(0)
	v_add_f32_e32 v31, v31, v36
	ds_bpermute_b32 v36, v45, v31
	s_waitcnt lgkmcnt(0)
	v_add_f32_e32 v31, v31, v36
	ds_bpermute_b32 v36, v46, v31
	s_waitcnt lgkmcnt(0)
	v_add_f32_e32 v31, v31, v36
	ds_bpermute_b32 v36, v47, v31
	s_waitcnt lgkmcnt(0)
	v_add_f32_e32 v31, v31, v36
	ds_bpermute_b32 v38, v48, v31
	v_mov_b32_e32 v36, v12
	s_waitcnt lgkmcnt(0)
	v_add_f32_e32 v12, v31, v38
	v_fmamk_f32 v12, v12, 0x3a800000, v70
	v_mul_f32_e32 v14, 0x4b800000, v12
	v_cmp_gt_f32_e32 vcc, s89, v12
	s_nop 1
	v_cndmask_b32_e32 v12, v12, v14, vcc
	v_rsq_f32_e32 v12, v12
	v_mov_b32_e32 v14, v13
	v_mul_f32_e32 v13, 0x45800000, v12
	v_cndmask_b32_e32 v30, v12, v13, vcc
	v_pk_mul_f32 v[12:13], v[36:37], v[30:31] op_sel_hi:[1,0]
	v_pk_mul_f32 v[14:15], v[14:15], v[30:31] op_sel_hi:[1,0]
	v_mov_b32_e32 v37, v20
	v_mov_b32_e32 v20, v19
	v_mov_b32_e32 v36, v18
	v_pk_mul_f32 v[14:15], v[20:21], v[14:15]
	v_mov_b32_e32 v20, v32
	v_mov_b32_e32 v21, v34
	v_pk_mul_f32 v[12:13], v[36:37], v[12:13]
	v_mov_b32_e32 v18, v22
	v_mov_b32_e32 v19, v24
	v_mov_b32_e32 v34, v33
	v_pk_add_f32 v[20:21], v[20:21], 1.0 op_sel_hi:[1,0]
	v_mov_b32_e32 v24, v23
	v_pk_fma_f32 v[12:13], v[12:13], v[20:21], v[18:19]
	v_pk_add_f32 v[18:19], v[34:35], 1.0 op_sel_hi:[1,0]
	v_mov_b32_e32 v32, v8
	v_pk_fma_f32 v[14:15], v[14:15], v[18:19], v[24:25]
	v_and_b32_sdwa v18, v13, v73 dst_sel:DWORD dst_unused:UNUSED_PAD src0_sel:WORD_1 src1_sel:DWORD
	v_and_b32_sdwa v19, v12, v73 dst_sel:DWORD dst_unused:UNUSED_PAD src0_sel:WORD_1 src1_sel:DWORD
	v_add3_u32 v12, v12, v19, s87
	v_add3_u32 v13, v13, v18, s87
	v_and_b32_sdwa v18, v15, v73 dst_sel:DWORD dst_unused:UNUSED_PAD src0_sel:WORD_1 src1_sel:DWORD
	v_and_b32_sdwa v19, v14, v73 dst_sel:DWORD dst_unused:UNUSED_PAD src0_sel:WORD_1 src1_sel:DWORD
	v_add3_u32 v15, v15, v18, s87
	v_add3_u32 v14, v14, v19, s87
	v_and_b32_e32 v15, 0xffff0000, v15
	v_and_b32_e32 v14, 0xffff0000, v14
	v_or_b32_sdwa v13, v15, v13 dst_sel:DWORD dst_unused:UNUSED_PAD src0_sel:DWORD src1_sel:WORD_1
	v_or_b32_sdwa v12, v14, v12 dst_sel:DWORD dst_unused:UNUSED_PAD src0_sel:DWORD src1_sel:WORD_1
	global_store_dwordx2 v[26:27], v[12:13], off
	v_mov_b64_e32 v[12:13], v[198:199]
	v_mov_b64_e32 v[14:15], v[200:201]
	s_nop 0
	v_mov_b64_e32 v[18:19], v[206:207]
	v_mov_b64_e32 v[20:21], v[208:209]
	v_mov_b64_e32 v[22:23], v[202:203]
	v_mov_b64_e32 v[24:25], v[204:205]
	v_mov_b32_e32 v33, v10
	v_mov_b32_e32 v10, v9
	v_pk_mul_f32 v[8:9], v[32:33], v[30:31] op_sel_hi:[1,0]
	v_pk_mul_f32 v[10:11], v[10:11], v[30:31] op_sel_hi:[1,0]
	v_mov_b32_e32 v33, v14
	s_waitcnt lgkmcnt(0)
; __device__ __forceinline__ unsigned pack2(float a, float b) { return (unsigned)f2bf(a) | ((unsigned)f2bf(b) << 16); }
; __device__ __forceinline__ void norm_job(const Params& p, int l, int job, bool from_x) {
;     ...
; #pragma unroll
;     for (int q = 0; q < 4; ++q) {
;       int col = lane * 4 + 256 * q;
;       float4 w = *(const float4*)&nw[col];
;       float4 sh = *(const float4*)&mods[col];
;       float4 sc = *(const float4*)&mods[1024 + col];
;       float o0 = xv[q].x * rstd * w.x * (1.f + sc.x) + sh.x;
;       float o1 = xv[q].y * rstd * w.y * (1.f + sc.y) + sh.y;
;       float o2 = xv[q].z * rstd * w.z * (1.f + sc.z) + sh.z;
;       float o3 = xv[q].w * rstd * w.w * (1.f + sc.w) + sh.w;
;       uint2 o; o.x = pack2(o0, o1); o.y = pack2(o2, o3);
;       *(uint2*)&HL[(size_t)row * 1024 + col] = o;
;     }
	v_mov_b32_e32 v35, v20
	v_mov_b32_e32 v14, v13
	v_mov_b32_e32 v20, v19
	v_mov_b32_e32 v32, v12
	v_mov_b32_e32 v34, v18
	v_mov_b32_e32 v37, v24
	v_mov_b32_e32 v24, v23
	v_pk_mul_f32 v[10:11], v[10:11], v[14:15]
	v_pk_add_f32 v[14:15], v[20:21], 1.0 op_sel_hi:[1,0]
	v_mov_b32_e32 v36, v22
	v_pk_mul_f32 v[8:9], v[8:9], v[32:33]
	v_pk_add_f32 v[12:13], v[34:35], 1.0 op_sel_hi:[1,0]
	v_pk_fma_f32 v[10:11], v[10:11], v[14:15], v[24:25]
	v_pk_fma_f32 v[8:9], v[8:9], v[12:13], v[36:37]
	v_and_b32_sdwa v14, v11, v73 dst_sel:DWORD dst_unused:UNUSED_PAD src0_sel:WORD_1 src1_sel:DWORD
	v_and_b32_sdwa v15, v10, v73 dst_sel:DWORD dst_unused:UNUSED_PAD src0_sel:WORD_1 src1_sel:DWORD
	v_and_b32_sdwa v12, v9, v73 dst_sel:DWORD dst_unused:UNUSED_PAD src0_sel:WORD_1 src1_sel:DWORD
	v_and_b32_sdwa v13, v8, v73 dst_sel:DWORD dst_unused:UNUSED_PAD src0_sel:WORD_1 src1_sel:DWORD
	v_add3_u32 v11, v11, v14, s87
	v_add3_u32 v10, v10, v15, s87
	v_add3_u32 v8, v8, v13, s87
	v_add3_u32 v9, v9, v12, s87
	v_and_b32_e32 v11, 0xffff0000, v11
	v_and_b32_e32 v10, 0xffff0000, v10
	v_or_b32_sdwa v9, v11, v9 dst_sel:DWORD dst_unused:UNUSED_PAD src0_sel:DWORD src1_sel:WORD_1
	v_or_b32_sdwa v8, v10, v8 dst_sel:DWORD dst_unused:UNUSED_PAD src0_sel:DWORD src1_sel:WORD_1
	global_store_dwordx2 v[26:27], v[8:9], off offset:512
	v_mov_b64_e32 v[8:9], v[210:211]
	v_mov_b64_e32 v[10:11], v[212:213]
	s_nop 0
	v_mov_b64_e32 v[12:13], v[218:219]
	v_mov_b64_e32 v[14:15], v[220:221]
	v_mov_b64_e32 v[18:19], v[214:215]
	v_mov_b64_e32 v[20:21], v[216:217]
	v_mov_b32_e32 v22, v0
	v_mov_b32_e32 v23, v2
	v_mov_b32_e32 v2, v1
	v_pk_mul_f32 v[0:1], v[22:23], v[30:31] op_sel_hi:[1,0]
	v_pk_mul_f32 v[2:3], v[2:3], v[30:31] op_sel_hi:[1,0]
	v_mov_b32_e32 v23, v10
	s_waitcnt lgkmcnt(0)
	v_mov_b32_e32 v25, v14
	v_mov_b32_e32 v10, v9
	v_mov_b32_e32 v14, v13
	v_mov_b32_e32 v22, v8
	v_mov_b32_e32 v24, v12
	v_mov_b32_e32 v33, v20
	v_mov_b32_e32 v20, v19
	v_pk_mul_f32 v[2:3], v[2:3], v[10:11]
	v_pk_add_f32 v[10:11], v[14:15], 1.0 op_sel_hi:[1,0]
	v_mov_b32_e32 v32, v18
	v_pk_mul_f32 v[0:1], v[0:1], v[22:23]
	v_pk_add_f32 v[8:9], v[24:25], 1.0 op_sel_hi:[1,0]
	v_pk_fma_f32 v[2:3], v[2:3], v[10:11], v[20:21]
	v_pk_fma_f32 v[0:1], v[0:1], v[8:9], v[32:33]
	v_and_b32_sdwa v10, v3, v73 dst_sel:DWORD dst_unused:UNUSED_PAD src0_sel:WORD_1 src1_sel:DWORD
	v_and_b32_sdwa v11, v2, v73 dst_sel:DWORD dst_unused:UNUSED_PAD src0_sel:WORD_1 src1_sel:DWORD
	v_and_b32_sdwa v8, v1, v73 dst_sel:DWORD dst_unused:UNUSED_PAD src0_sel:WORD_1 src1_sel:DWORD
	v_and_b32_sdwa v9, v0, v73 dst_sel:DWORD dst_unused:UNUSED_PAD src0_sel:WORD_1 src1_sel:DWORD
	v_add3_u32 v3, v3, v10, s87
	v_add3_u32 v2, v2, v11, s87
	v_add3_u32 v0, v0, v9, s87
	v_add3_u32 v1, v1, v8, s87
	v_and_b32_e32 v3, 0xffff0000, v3
	v_and_b32_e32 v2, 0xffff0000, v2
	v_or_b32_sdwa v1, v3, v1 dst_sel:DWORD dst_unused:UNUSED_PAD src0_sel:DWORD src1_sel:WORD_1
	v_or_b32_sdwa v0, v2, v0 dst_sel:DWORD dst_unused:UNUSED_PAD src0_sel:DWORD src1_sel:WORD_1
	global_store_dwordx2 v[26:27], v[0:1], off offset:1024
	v_mov_b64_e32 v[0:1], v[222:223]
	v_mov_b64_e32 v[2:3], v[224:225]
	s_nop 0
	v_mov_b64_e32 v[8:9], v[230:231]
	v_mov_b64_e32 v[10:11], v[232:233]
	v_mov_b64_e32 v[12:13], v[226:227]
	v_mov_b64_e32 v[14:15], v[228:229]
	v_mov_b32_e32 v16, v4
	v_mov_b32_e32 v17, v6
	v_mov_b32_e32 v6, v5
	v_pk_mul_f32 v[4:5], v[16:17], v[30:31] op_sel_hi:[1,0]
	v_pk_mul_f32 v[6:7], v[6:7], v[30:31] op_sel_hi:[1,0]
	v_mov_b32_e32 v17, v2
	s_waitcnt lgkmcnt(0)
	v_mov_b32_e32 v19, v10
	v_mov_b32_e32 v2, v1
	v_mov_b32_e32 v10, v9
	v_mov_b32_e32 v16, v0
	v_mov_b32_e32 v18, v8
	v_mov_b32_e32 v21, v14
	v_mov_b32_e32 v14, v13
	v_pk_mul_f32 v[2:3], v[6:7], v[2:3]
	v_pk_add_f32 v[6:7], v[10:11], 1.0 op_sel_hi:[1,0]
	v_mov_b32_e32 v20, v12
	v_pk_mul_f32 v[0:1], v[4:5], v[16:17]
	v_pk_add_f32 v[4:5], v[18:19], 1.0 op_sel_hi:[1,0]
	v_pk_fma_f32 v[2:3], v[2:3], v[6:7], v[14:15]
	v_pk_fma_f32 v[0:1], v[0:1], v[4:5], v[20:21]
	v_and_b32_sdwa v6, v3, v73 dst_sel:DWORD dst_unused:UNUSED_PAD src0_sel:WORD_1 src1_sel:DWORD
	v_and_b32_sdwa v7, v2, v73 dst_sel:DWORD dst_unused:UNUSED_PAD src0_sel:WORD_1 src1_sel:DWORD
	v_and_b32_sdwa v4, v1, v73 dst_sel:DWORD dst_unused:UNUSED_PAD src0_sel:WORD_1 src1_sel:DWORD
	v_and_b32_sdwa v5, v0, v73 dst_sel:DWORD dst_unused:UNUSED_PAD src0_sel:WORD_1 src1_sel:DWORD
	v_add3_u32 v3, v3, v6, s87
	v_add3_u32 v2, v2, v7, s87
	v_add3_u32 v0, v0, v5, s87
	v_add3_u32 v1, v1, v4, s87
	v_and_b32_e32 v3, 0xffff0000, v3
	v_and_b32_e32 v2, 0xffff0000, v2
	v_or_b32_sdwa v1, v3, v1 dst_sel:DWORD dst_unused:UNUSED_PAD src0_sel:DWORD src1_sel:WORD_1
	v_or_b32_sdwa v0, v2, v0 dst_sel:DWORD dst_unused:UNUSED_PAD src0_sel:DWORD src1_sel:WORD_1
	global_store_dwordx2 v[26:27], v[0:1], off offset:1536
	s_branch .LBB0_156

; __device__ __forceinline__ void outproj_tile(const Params& p, char* smem, int l, int mt, int nt, int ks) {
;     ...
;   auto epi = [&](f32x4 (&acc)[8][4], int wr, int wc, int fr, int fq) {
;     const int row0 = mt * 256;
;     const int v = row0 < MLAT ? (row0 >> 13) : 2;
;     float* O = l == 0 ? XN : p.out;
;     float gv[4];
; #pragma unroll
;     for (int n = 0; n < 4; ++n) gv[n] = MODS[(l * 3 + v) * 6144 + 2048 + nt * 128 + wc * 64 + n * 16 + fr];
; #pragma unroll
;     for (int m = 0; m < 8; ++m)
; #pragma unroll
;       for (int j = 0; j < 4; ++j) {
;         int row = row0 + wr * 128 + m * 16 + fq * 4 + j;
;         float* orow = O + (size_t)row * 1024 + nt * 128 + wc * 64 + fr;
; #pragma unroll
;         for (int n = 0; n < 4; ++n) unsafeAtomicAdd(orow + n * 16, gv[n] * acc[m][n][j]);
;       }
;   };
.LBB0_1194:
	v_ashrrev_i32_e32 v3, 31, v2
	v_lshl_add_u64 v[2:3], v[2:3], 2, s[0:1]
	s_mov_b64 s[0:1], 0x18e00000
	s_waitcnt vmcnt(0)
	v_lshl_add_u64 v[134:135], v[2:3], 0, s[0:1]
	v_add_co_u32_e32 v2, vcc, 0x18e00000, v2
	global_load_dword v138, v[134:135], off offset:192
	global_load_dword v139, v[134:135], off offset:128
	global_load_dword v140, v[134:135], off offset:64
	v_addc_co_u32_e32 v3, vcc, 0, v3, vcc
	global_load_dword v141, v[2:3], off
	v_lshlrev_b32_e32 v2, 2, v157
	v_and_or_b32 v2, v2, 12, v133
	v_ashrrev_i32_e32 v3, 31, v2
	v_lshlrev_b64 v[134:135], 12, v[2:3]
	v_mov_b32_e32 v133, v1
	v_lshl_add_u64 v[134:135], s[12:13], 0, v[134:135]
	v_lshlrev_b64 v[132:133], 2, v[132:133]
	v_mov_b32_e32 v157, v1
	v_lshl_add_u64 v[136:137], v[134:135], 0, v[132:133]
	v_lshlrev_b64 v[134:135], 2, v[0:1]
	v_lshl_add_u64 v[142:143], v[136:137], 0, v[134:135]
	v_lshlrev_b64 v[136:137], 2, v[156:157]
	v_lshl_add_u64 v[142:143], v[142:143], 0, v[136:137]
	v_readlane_b32 s0, v239, 1
	v_readlane_b32 s1, v239, 2
	s_add_i32 s17, s17, s0
	s_waitcnt vmcnt(0) lgkmcnt(0)
	s_sub_i32 s6, s17, s0
	s_cmpk_lt_i32 s6, 0x200
	s_cbranch_scc0 .Lp3_atomic
	v_readlane_b32 s6, v239, 63
	v_readlane_b32 s100, v239, 7
	v_readlane_b32 s101, v239, 8
	s_cmp_eq_u32 s6, 0
	s_cbranch_scc1 .Lp3_src_x
	s_add_u32 s100, s58, 0x2a196100
	s_addc_u32 s101, s59, 0
.Lp3_src_x:
	v_lshlrev_b32_e32 v142, 12, v2
	v_add3_u32 v142, v142, v132, v134
	v_add_u32_e32 v142, v142, v136
	v_add_u32_e32 v132, 0x0, v142
	v_add_u32_e32 v133, 0x1000, v142
	v_add_u32_e32 v134, 0x2000, v142
	v_add_u32_e32 v135, 0x3000, v142
	global_load_dword v240, v132, s[100:101]
	global_load_dword v241, v132, s[100:101] offset:64
	global_load_dword v242, v132, s[100:101] offset:128
	global_load_dword v243, v132, s[100:101] offset:192
	global_load_dword v244, v133, s[100:101]
	global_load_dword v245, v133, s[100:101] offset:64
	global_load_dword v246, v133, s[100:101] offset:128
	global_load_dword v247, v133, s[100:101] offset:192
	global_load_dword v248, v134, s[100:101]
	global_load_dword v249, v134, s[100:101] offset:64
	global_load_dword v250, v134, s[100:101] offset:128
	global_load_dword v251, v134, s[100:101] offset:192
	global_load_dword v252, v135, s[100:101]
	global_load_dword v253, v135, s[100:101] offset:64
	global_load_dword v254, v135, s[100:101] offset:128
	global_load_dword v255, v135, s[100:101] offset:192
	v_add_u32_e32 v136, 0x10000, v142
	v_add_u32_e32 v137, 0x11000, v142
	v_add_u32_e32 v143, 0x12000, v142
	v_add_u32_e32 v3, 0x13000, v142
	global_load_dword v144, v136, s[100:101]
	global_load_dword v145, v136, s[100:101] offset:64
	global_load_dword v146, v136, s[100:101] offset:128
	global_load_dword v147, v136, s[100:101] offset:192
	global_load_dword v148, v137, s[100:101]
	global_load_dword v149, v137, s[100:101] offset:64
	global_load_dword v150, v137, s[100:101] offset:128
	global_load_dword v151, v137, s[100:101] offset:192
	global_load_dword v152, v143, s[100:101]
	global_load_dword v153, v143, s[100:101] offset:64
	global_load_dword v154, v143, s[100:101] offset:128
	global_load_dword v155, v143, s[100:101] offset:192
	global_load_dword v232, v3, s[100:101]
	global_load_dword v233, v3, s[100:101] offset:64
	global_load_dword v234, v3, s[100:101] offset:128
	global_load_dword v235, v3, s[100:101] offset:192
	s_waitcnt vmcnt(16)
	v_mul_f32_e32 v128, v128, v141
	v_mul_f32_e32 v124, v124, v140
	v_mul_f32_e32 v120, v120, v139
	v_mul_f32_e32 v116, v116, v138
	v_mul_f32_e32 v129, v129, v141
	v_mul_f32_e32 v125, v125, v140
	v_mul_f32_e32 v121, v121, v139
	v_mul_f32_e32 v117, v117, v138
	v_mul_f32_e32 v130, v130, v141
	v_mul_f32_e32 v126, v126, v140
	v_mul_f32_e32 v122, v122, v139
	v_mul_f32_e32 v118, v118, v138
	v_mul_f32_e32 v131, v131, v141
	v_mul_f32_e32 v127, v127, v140
	v_mul_f32_e32 v123, v123, v139
	v_mul_f32_e32 v119, v119, v138
	v_add_f32_e32 v128, v240, v128
	v_add_f32_e32 v124, v241, v124
	v_add_f32_e32 v120, v242, v120
	v_add_f32_e32 v116, v243, v116
	v_add_f32_e32 v129, v244, v129
	v_add_f32_e32 v125, v245, v125
	v_add_f32_e32 v121, v246, v121
	v_add_f32_e32 v117, v247, v117
	v_add_f32_e32 v130, v248, v130
	v_add_f32_e32 v126, v249, v126
	v_add_f32_e32 v122, v250, v122
	v_add_f32_e32 v118, v251, v118
	v_add_f32_e32 v131, v252, v131
	v_add_f32_e32 v127, v253, v127
	v_add_f32_e32 v123, v254, v123
	v_add_f32_e32 v119, v255, v119
	v_add_u32_e32 v132, 0x20000, v142
	v_add_u32_e32 v133, 0x21000, v142
	v_add_u32_e32 v134, 0x22000, v142
	v_add_u32_e32 v135, 0x23000, v142
	global_load_dword v240, v132, s[100:101]
	global_load_dword v241, v132, s[100:101] offset:64
	global_load_dword v242, v132, s[100:101] offset:128
	global_load_dword v243, v132, s[100:101] offset:192
	global_load_dword v244, v133, s[100:101]
	global_load_dword v245, v133, s[100:101] offset:64
	global_load_dword v246, v133, s[100:101] offset:128
	global_load_dword v247, v133, s[100:101] offset:192
	global_load_dword v248, v134, s[100:101]
	global_load_dword v249, v134, s[100:101] offset:64
	global_load_dword v250, v134, s[100:101] offset:128
	global_load_dword v251, v134, s[100:101] offset:192
	global_load_dword v252, v135, s[100:101]
	global_load_dword v253, v135, s[100:101] offset:64
	global_load_dword v254, v135, s[100:101] offset:128
	global_load_dword v255, v135, s[100:101] offset:192
	s_waitcnt vmcnt(16)
; __device__ __forceinline__ void outproj_tile(const Params& p, char* smem, int l, int mt, int nt, int ks) {
;     ...
;   auto epi = [&](f32x4 (&acc)[8][4], int wr, int wc, int fr, int fq) {
;     const int row0 = mt * 256;
;     const int v = row0 < MLAT ? (row0 >> 13) : 2;
;     float* O = l == 0 ? XN : p.out;
;     float gv[4];
; #pragma unroll
;     for (int n = 0; n < 4; ++n) gv[n] = MODS[(l * 3 + v) * 6144 + 2048 + nt * 128 + wc * 64 + n * 16 + fr];
; #pragma unroll
;     for (int m = 0; m < 8; ++m)
; #pragma unroll
;       for (int j = 0; j < 4; ++j) {
;         int row = row0 + wr * 128 + m * 16 + fq * 4 + j;
;         float* orow = O + (size_t)row * 1024 + nt * 128 + wc * 64 + fr;
; #pragma unroll
;         for (int n = 0; n < 4; ++n) unsafeAtomicAdd(orow + n * 16, gv[n] * acc[m][n][j]);
;       }
;   };
	v_mul_f32_e32 v112, v112, v141
	v_mul_f32_e32 v108, v108, v140
	v_mul_f32_e32 v104, v104, v139
	v_mul_f32_e32 v100, v100, v138
	v_mul_f32_e32 v113, v113, v141
	v_mul_f32_e32 v109, v109, v140
	v_mul_f32_e32 v105, v105, v139
	v_mul_f32_e32 v101, v101, v138
	v_mul_f32_e32 v114, v114, v141
	v_mul_f32_e32 v110, v110, v140
	v_mul_f32_e32 v106, v106, v139
	v_mul_f32_e32 v102, v102, v138
	v_mul_f32_e32 v115, v115, v141
	v_mul_f32_e32 v111, v111, v140
	v_mul_f32_e32 v107, v107, v139
	v_mul_f32_e32 v103, v103, v138
	v_add_f32_e32 v112, v144, v112
	v_add_f32_e32 v108, v145, v108
	v_add_f32_e32 v104, v146, v104
	v_add_f32_e32 v100, v147, v100
	v_add_f32_e32 v113, v148, v113
	v_add_f32_e32 v109, v149, v109
	v_add_f32_e32 v105, v150, v105
	v_add_f32_e32 v101, v151, v101
	v_add_f32_e32 v114, v152, v114
	v_add_f32_e32 v110, v153, v110
	v_add_f32_e32 v106, v154, v106
	v_add_f32_e32 v102, v155, v102
	v_add_f32_e32 v115, v232, v115
	v_add_f32_e32 v111, v233, v111
	v_add_f32_e32 v107, v234, v107
	v_add_f32_e32 v103, v235, v103
	v_add_u32_e32 v136, 0x30000, v142
	v_add_u32_e32 v137, 0x31000, v142
	v_add_u32_e32 v143, 0x32000, v142
	v_add_u32_e32 v3, 0x33000, v142
	global_load_dword v144, v136, s[100:101]
	global_load_dword v145, v136, s[100:101] offset:64
	global_load_dword v146, v136, s[100:101] offset:128
	global_load_dword v147, v136, s[100:101] offset:192
	global_load_dword v148, v137, s[100:101]
	global_load_dword v149, v137, s[100:101] offset:64
	global_load_dword v150, v137, s[100:101] offset:128
	global_load_dword v151, v137, s[100:101] offset:192
	global_load_dword v152, v143, s[100:101]
	global_load_dword v153, v143, s[100:101] offset:64
	global_load_dword v154, v143, s[100:101] offset:128
	global_load_dword v155, v143, s[100:101] offset:192
	global_load_dword v232, v3, s[100:101]
	global_load_dword v233, v3, s[100:101] offset:64
	global_load_dword v234, v3, s[100:101] offset:128
	global_load_dword v235, v3, s[100:101] offset:192
	s_waitcnt vmcnt(16)
	v_mul_f32_e32 v96, v96, v141
	v_mul_f32_e32 v92, v92, v140
	v_mul_f32_e32 v88, v88, v139
	v_mul_f32_e32 v84, v84, v138
	v_mul_f32_e32 v97, v97, v141
	v_mul_f32_e32 v93, v93, v140
	v_mul_f32_e32 v89, v89, v139
	v_mul_f32_e32 v85, v85, v138
	v_mul_f32_e32 v98, v98, v141
	v_mul_f32_e32 v94, v94, v140
	v_mul_f32_e32 v90, v90, v139
	v_mul_f32_e32 v86, v86, v138
	v_mul_f32_e32 v99, v99, v141
	v_mul_f32_e32 v95, v95, v140
	v_mul_f32_e32 v91, v91, v139
	v_mul_f32_e32 v87, v87, v138
	v_add_f32_e32 v96, v240, v96
	v_add_f32_e32 v92, v241, v92
	v_add_f32_e32 v88, v242, v88
	v_add_f32_e32 v84, v243, v84
	v_add_f32_e32 v97, v244, v97
	v_add_f32_e32 v93, v245, v93
	v_add_f32_e32 v89, v246, v89
	v_add_f32_e32 v85, v247, v85
	v_add_f32_e32 v98, v248, v98
	v_add_f32_e32 v94, v249, v94
	v_add_f32_e32 v90, v250, v90
	v_add_f32_e32 v86, v251, v86
	v_add_f32_e32 v99, v252, v99
	v_add_f32_e32 v95, v253, v95
	v_add_f32_e32 v91, v254, v91
	v_add_f32_e32 v87, v255, v87
	v_add_u32_e32 v132, 0x40000, v142
	v_add_u32_e32 v133, 0x41000, v142
	v_add_u32_e32 v134, 0x42000, v142
	v_add_u32_e32 v135, 0x43000, v142
	global_load_dword v240, v132, s[100:101]
	global_load_dword v241, v132, s[100:101] offset:64
	global_load_dword v242, v132, s[100:101] offset:128
	global_load_dword v243, v132, s[100:101] offset:192
	global_load_dword v244, v133, s[100:101]
	global_load_dword v245, v133, s[100:101] offset:64
	global_load_dword v246, v133, s[100:101] offset:128
	global_load_dword v247, v133, s[100:101] offset:192
	global_load_dword v248, v134, s[100:101]
	global_load_dword v249, v134, s[100:101] offset:64
	global_load_dword v250, v134, s[100:101] offset:128
	global_load_dword v251, v134, s[100:101] offset:192
	global_load_dword v252, v135, s[100:101]
	global_load_dword v253, v135, s[100:101] offset:64
	global_load_dword v254, v135, s[100:101] offset:128
	global_load_dword v255, v135, s[100:101] offset:192
	s_waitcnt vmcnt(16)
	v_mul_f32_e32 v80, v80, v141
	v_mul_f32_e32 v76, v76, v140
	v_mul_f32_e32 v72, v72, v139
	v_mul_f32_e32 v68, v68, v138
	v_mul_f32_e32 v81, v81, v141
	v_mul_f32_e32 v77, v77, v140
	v_mul_f32_e32 v73, v73, v139
	v_mul_f32_e32 v69, v69, v138
	v_mul_f32_e32 v82, v82, v141
	v_mul_f32_e32 v78, v78, v140
	v_mul_f32_e32 v74, v74, v139
	v_mul_f32_e32 v70, v70, v138
	v_mul_f32_e32 v83, v83, v141
	v_mul_f32_e32 v79, v79, v140
	v_mul_f32_e32 v75, v75, v139
	v_mul_f32_e32 v71, v71, v138
	v_add_f32_e32 v80, v144, v80
	v_add_f32_e32 v76, v145, v76
	v_add_f32_e32 v72, v146, v72
	v_add_f32_e32 v68, v147, v68
	v_add_f32_e32 v81, v148, v81
	v_add_f32_e32 v77, v149, v77
	v_add_f32_e32 v73, v150, v73
	v_add_f32_e32 v69, v151, v69
	v_add_f32_e32 v82, v152, v82
	v_add_f32_e32 v78, v153, v78
	v_add_f32_e32 v74, v154, v74
	v_add_f32_e32 v70, v155, v70
	v_add_f32_e32 v83, v232, v83
	v_add_f32_e32 v79, v233, v79
	v_add_f32_e32 v75, v234, v75
	v_add_f32_e32 v71, v235, v71
	v_add_u32_e32 v136, 0x50000, v142
	v_add_u32_e32 v137, 0x51000, v142
	v_add_u32_e32 v143, 0x52000, v142
	v_add_u32_e32 v3, 0x53000, v142
	global_load_dword v144, v136, s[100:101]
	global_load_dword v145, v136, s[100:101] offset:64
	global_load_dword v146, v136, s[100:101] offset:128
	global_load_dword v147, v136, s[100:101] offset:192
	global_load_dword v148, v137, s[100:101]
	global_load_dword v149, v137, s[100:101] offset:64
	global_load_dword v150, v137, s[100:101] offset:128
	global_load_dword v151, v137, s[100:101] offset:192
	global_load_dword v152, v143, s[100:101]
	global_load_dword v153, v143, s[100:101] offset:64
	global_load_dword v154, v143, s[100:101] offset:128
	global_load_dword v155, v143, s[100:101] offset:192
	global_load_dword v232, v3, s[100:101]
	global_load_dword v233, v3, s[100:101] offset:64
	global_load_dword v234, v3, s[100:101] offset:128
	global_load_dword v235, v3, s[100:101] offset:192
	s_waitcnt vmcnt(16)
; __device__ __forceinline__ void outproj_tile(const Params& p, char* smem, int l, int mt, int nt, int ks) {
;     ...
;   auto epi = [&](f32x4 (&acc)[8][4], int wr, int wc, int fr, int fq) {
;     const int row0 = mt * 256;
;     const int v = row0 < MLAT ? (row0 >> 13) : 2;
;     float* O = l == 0 ? XN : p.out;
;     float gv[4];
; #pragma unroll
;     for (int n = 0; n < 4; ++n) gv[n] = MODS[(l * 3 + v) * 6144 + 2048 + nt * 128 + wc * 64 + n * 16 + fr];
; #pragma unroll
;     for (int m = 0; m < 8; ++m)
; #pragma unroll
;       for (int j = 0; j < 4; ++j) {
;         int row = row0 + wr * 128 + m * 16 + fq * 4 + j;
;         float* orow = O + (size_t)row * 1024 + nt * 128 + wc * 64 + fr;
; #pragma unroll
;         for (int n = 0; n < 4; ++n) unsafeAtomicAdd(orow + n * 16, gv[n] * acc[m][n][j]);
;       }
;   };
	v_mul_f32_e32 v64, v64, v141
	v_mul_f32_e32 v60, v60, v140
	v_mul_f32_e32 v56, v56, v139
	v_mul_f32_e32 v52, v52, v138
	v_mul_f32_e32 v65, v65, v141
	v_mul_f32_e32 v61, v61, v140
	v_mul_f32_e32 v57, v57, v139
	v_mul_f32_e32 v53, v53, v138
	v_mul_f32_e32 v66, v66, v141
	v_mul_f32_e32 v62, v62, v140
	v_mul_f32_e32 v58, v58, v139
	v_mul_f32_e32 v54, v54, v138
	v_mul_f32_e32 v67, v67, v141
	v_mul_f32_e32 v63, v63, v140
	v_mul_f32_e32 v59, v59, v139
	v_mul_f32_e32 v55, v55, v138
	v_add_f32_e32 v64, v240, v64
	v_add_f32_e32 v60, v241, v60
	v_add_f32_e32 v56, v242, v56
	v_add_f32_e32 v52, v243, v52
	v_add_f32_e32 v65, v244, v65
	v_add_f32_e32 v61, v245, v61
	v_add_f32_e32 v57, v246, v57
	v_add_f32_e32 v53, v247, v53
	v_add_f32_e32 v66, v248, v66
	v_add_f32_e32 v62, v249, v62
	v_add_f32_e32 v58, v250, v58
	v_add_f32_e32 v54, v251, v54
	v_add_f32_e32 v67, v252, v67
	v_add_f32_e32 v63, v253, v63
	v_add_f32_e32 v59, v254, v59
	v_add_f32_e32 v55, v255, v55
	v_add_u32_e32 v132, 0x60000, v142
	v_add_u32_e32 v133, 0x61000, v142
	v_add_u32_e32 v134, 0x62000, v142
	v_add_u32_e32 v135, 0x63000, v142
	global_load_dword v240, v132, s[100:101]
	global_load_dword v241, v132, s[100:101] offset:64
	global_load_dword v242, v132, s[100:101] offset:128
	global_load_dword v243, v132, s[100:101] offset:192
	global_load_dword v244, v133, s[100:101]
	global_load_dword v245, v133, s[100:101] offset:64
	global_load_dword v246, v133, s[100:101] offset:128
	global_load_dword v247, v133, s[100:101] offset:192
	global_load_dword v248, v134, s[100:101]
	global_load_dword v249, v134, s[100:101] offset:64
	global_load_dword v250, v134, s[100:101] offset:128
	global_load_dword v251, v134, s[100:101] offset:192
	global_load_dword v252, v135, s[100:101]
	global_load_dword v253, v135, s[100:101] offset:64
	global_load_dword v254, v135, s[100:101] offset:128
	global_load_dword v255, v135, s[100:101] offset:192
	s_waitcnt vmcnt(16)
	v_mul_f32_e32 v48, v48, v141
	v_mul_f32_e32 v44, v44, v140
	v_mul_f32_e32 v40, v40, v139
	v_mul_f32_e32 v36, v36, v138
	v_mul_f32_e32 v49, v49, v141
	v_mul_f32_e32 v45, v45, v140
	v_mul_f32_e32 v41, v41, v139
	v_mul_f32_e32 v37, v37, v138
	v_mul_f32_e32 v50, v50, v141
	v_mul_f32_e32 v46, v46, v140
	v_mul_f32_e32 v42, v42, v139
	v_mul_f32_e32 v38, v38, v138
	v_mul_f32_e32 v51, v51, v141
	v_mul_f32_e32 v47, v47, v140
	v_mul_f32_e32 v43, v43, v139
	v_mul_f32_e32 v39, v39, v138
	v_add_f32_e32 v48, v144, v48
	v_add_f32_e32 v44, v145, v44
	v_add_f32_e32 v40, v146, v40
	v_add_f32_e32 v36, v147, v36
	v_add_f32_e32 v49, v148, v49
	v_add_f32_e32 v45, v149, v45
	v_add_f32_e32 v41, v150, v41
	v_add_f32_e32 v37, v151, v37
	v_add_f32_e32 v50, v152, v50
	v_add_f32_e32 v46, v153, v46
	v_add_f32_e32 v42, v154, v42
	v_add_f32_e32 v38, v155, v38
	v_add_f32_e32 v51, v232, v51
	v_add_f32_e32 v47, v233, v47
	v_add_f32_e32 v43, v234, v43
	v_add_f32_e32 v39, v235, v39
	v_add_u32_e32 v136, 0x70000, v142
	v_add_u32_e32 v137, 0x71000, v142
	v_add_u32_e32 v143, 0x72000, v142
	v_add_u32_e32 v3, 0x73000, v142
	global_load_dword v144, v136, s[100:101]
	global_load_dword v145, v136, s[100:101] offset:64
	global_load_dword v146, v136, s[100:101] offset:128
	global_load_dword v147, v136, s[100:101] offset:192
	global_load_dword v148, v137, s[100:101]
	global_load_dword v149, v137, s[100:101] offset:64
	global_load_dword v150, v137, s[100:101] offset:128
	global_load_dword v151, v137, s[100:101] offset:192
	global_load_dword v152, v143, s[100:101]
	global_load_dword v153, v143, s[100:101] offset:64
	global_load_dword v154, v143, s[100:101] offset:128
	global_load_dword v155, v143, s[100:101] offset:192
	global_load_dword v232, v3, s[100:101]
	global_load_dword v233, v3, s[100:101] offset:64
	global_load_dword v234, v3, s[100:101] offset:128
	global_load_dword v235, v3, s[100:101] offset:192
	s_waitcnt vmcnt(16)
	v_mul_f32_e32 v32, v32, v141
	v_mul_f32_e32 v28, v28, v140
	v_mul_f32_e32 v24, v24, v139
	v_mul_f32_e32 v20, v20, v138
	v_mul_f32_e32 v33, v33, v141
	v_mul_f32_e32 v29, v29, v140
	v_mul_f32_e32 v25, v25, v139
	v_mul_f32_e32 v21, v21, v138
	v_mul_f32_e32 v34, v34, v141
	v_mul_f32_e32 v30, v30, v140
	v_mul_f32_e32 v26, v26, v139
	v_mul_f32_e32 v22, v22, v138
	v_mul_f32_e32 v35, v35, v141
	v_mul_f32_e32 v31, v31, v140
	v_mul_f32_e32 v27, v27, v139
	v_mul_f32_e32 v23, v23, v138
	v_add_f32_e32 v32, v240, v32
	v_add_f32_e32 v28, v241, v28
	v_add_f32_e32 v24, v242, v24
	v_add_f32_e32 v20, v243, v20
	v_add_f32_e32 v33, v244, v33
	v_add_f32_e32 v29, v245, v29
	v_add_f32_e32 v25, v246, v25
	v_add_f32_e32 v21, v247, v21
	v_add_f32_e32 v34, v248, v34
	v_add_f32_e32 v30, v249, v30
	v_add_f32_e32 v26, v250, v26
	v_add_f32_e32 v22, v251, v22
	v_add_f32_e32 v35, v252, v35
	v_add_f32_e32 v31, v253, v31
	v_add_f32_e32 v27, v254, v27
	v_add_f32_e32 v23, v255, v23
	s_waitcnt vmcnt(0)
; __device__ __forceinline__ void outproj_tile(const Params& p, char* smem, int l, int mt, int nt, int ks) {
;     ...
;   auto epi = [&](f32x4 (&acc)[8][4], int wr, int wc, int fr, int fq) {
;     const int row0 = mt * 256;
;     const int v = row0 < MLAT ? (row0 >> 13) : 2;
;     float* O = l == 0 ? XN : p.out;
;     float gv[4];
; #pragma unroll
;     for (int n = 0; n < 4; ++n) gv[n] = MODS[(l * 3 + v) * 6144 + 2048 + nt * 128 + wc * 64 + n * 16 + fr];
; #pragma unroll
;     for (int m = 0; m < 8; ++m)
; #pragma unroll
;       for (int j = 0; j < 4; ++j) {
;         int row = row0 + wr * 128 + m * 16 + fq * 4 + j;
;         float* orow = O + (size_t)row * 1024 + nt * 128 + wc * 64 + fr;
; #pragma unroll
;         for (int n = 0; n < 4; ++n) unsafeAtomicAdd(orow + n * 16, gv[n] * acc[m][n][j]);
;       }
;   };
	v_mul_f32_e32 v16, v16, v141
	v_mul_f32_e32 v12, v12, v140
	v_mul_f32_e32 v8, v8, v139
	v_mul_f32_e32 v4, v4, v138
	v_mul_f32_e32 v17, v17, v141
	v_mul_f32_e32 v13, v13, v140
	v_mul_f32_e32 v9, v9, v139
	v_mul_f32_e32 v5, v5, v138
	v_mul_f32_e32 v18, v18, v141
	v_mul_f32_e32 v14, v14, v140
	v_mul_f32_e32 v10, v10, v139
	v_mul_f32_e32 v6, v6, v138
	v_mul_f32_e32 v19, v19, v141
	v_mul_f32_e32 v15, v15, v140
	v_mul_f32_e32 v11, v11, v139
	v_mul_f32_e32 v7, v7, v138
	v_add_f32_e32 v16, v144, v16
	v_add_f32_e32 v12, v145, v12
	v_add_f32_e32 v8, v146, v8
	v_add_f32_e32 v4, v147, v4
	v_add_f32_e32 v17, v148, v17
	v_add_f32_e32 v13, v149, v13
	v_add_f32_e32 v9, v150, v9
	v_add_f32_e32 v5, v151, v5
	v_add_f32_e32 v18, v152, v18
	v_add_f32_e32 v14, v153, v14
	v_add_f32_e32 v10, v154, v10
	v_add_f32_e32 v6, v155, v6
	v_add_f32_e32 v19, v232, v19
	v_add_f32_e32 v15, v233, v15
	v_add_f32_e32 v11, v234, v11
	v_add_f32_e32 v7, v235, v7
	v_add_u32_e32 v132, 0x0, v142
	global_store_dword v132, v128, s[12:13]
	global_store_dword v132, v124, s[12:13] offset:64
	global_store_dword v132, v120, s[12:13] offset:128
	global_store_dword v132, v116, s[12:13] offset:192
	v_add_u32_e32 v133, 0x1000, v142
	global_store_dword v133, v129, s[12:13]
	global_store_dword v133, v125, s[12:13] offset:64
	global_store_dword v133, v121, s[12:13] offset:128
	global_store_dword v133, v117, s[12:13] offset:192
	v_add_u32_e32 v134, 0x2000, v142
	global_store_dword v134, v130, s[12:13]
	global_store_dword v134, v126, s[12:13] offset:64
	global_store_dword v134, v122, s[12:13] offset:128
	global_store_dword v134, v118, s[12:13] offset:192
	v_add_u32_e32 v135, 0x3000, v142
	global_store_dword v135, v131, s[12:13]
	global_store_dword v135, v127, s[12:13] offset:64
	global_store_dword v135, v123, s[12:13] offset:128
	global_store_dword v135, v119, s[12:13] offset:192
	v_add_u32_e32 v132, 0x10000, v142
	global_store_dword v132, v112, s[12:13]
	global_store_dword v132, v108, s[12:13] offset:64
	global_store_dword v132, v104, s[12:13] offset:128
	global_store_dword v132, v100, s[12:13] offset:192
	v_add_u32_e32 v133, 0x11000, v142
	global_store_dword v133, v113, s[12:13]
	global_store_dword v133, v109, s[12:13] offset:64
	global_store_dword v133, v105, s[12:13] offset:128
	global_store_dword v133, v101, s[12:13] offset:192
	v_add_u32_e32 v134, 0x12000, v142
	global_store_dword v134, v114, s[12:13]
	global_store_dword v134, v110, s[12:13] offset:64
	global_store_dword v134, v106, s[12:13] offset:128
	global_store_dword v134, v102, s[12:13] offset:192
	v_add_u32_e32 v135, 0x13000, v142
	global_store_dword v135, v115, s[12:13]
	global_store_dword v135, v111, s[12:13] offset:64
	global_store_dword v135, v107, s[12:13] offset:128
	global_store_dword v135, v103, s[12:13] offset:192
	v_add_u32_e32 v132, 0x20000, v142
	global_store_dword v132, v96, s[12:13]
	global_store_dword v132, v92, s[12:13] offset:64
	global_store_dword v132, v88, s[12:13] offset:128
	global_store_dword v132, v84, s[12:13] offset:192
	v_add_u32_e32 v133, 0x21000, v142
	global_store_dword v133, v97, s[12:13]
	global_store_dword v133, v93, s[12:13] offset:64
	global_store_dword v133, v89, s[12:13] offset:128
	global_store_dword v133, v85, s[12:13] offset:192
	v_add_u32_e32 v134, 0x22000, v142
	global_store_dword v134, v98, s[12:13]
	global_store_dword v134, v94, s[12:13] offset:64
	global_store_dword v134, v90, s[12:13] offset:128
	global_store_dword v134, v86, s[12:13] offset:192
	v_add_u32_e32 v135, 0x23000, v142
	global_store_dword v135, v99, s[12:13]
	global_store_dword v135, v95, s[12:13] offset:64
	global_store_dword v135, v91, s[12:13] offset:128
	global_store_dword v135, v87, s[12:13] offset:192
	v_add_u32_e32 v132, 0x30000, v142
	global_store_dword v132, v80, s[12:13]
	global_store_dword v132, v76, s[12:13] offset:64
	global_store_dword v132, v72, s[12:13] offset:128
	global_store_dword v132, v68, s[12:13] offset:192
	v_add_u32_e32 v133, 0x31000, v142
	global_store_dword v133, v81, s[12:13]
	global_store_dword v133, v77, s[12:13] offset:64
	global_store_dword v133, v73, s[12:13] offset:128
	global_store_dword v133, v69, s[12:13] offset:192
; __device__ __forceinline__ void outproj_tile(const Params& p, char* smem, int l, int mt, int nt, int ks) {
;     ...
;   auto epi = [&](f32x4 (&acc)[8][4], int wr, int wc, int fr, int fq) {
;     const int row0 = mt * 256;
;     const int v = row0 < MLAT ? (row0 >> 13) : 2;
;     float* O = l == 0 ? XN : p.out;
;     float gv[4];
; #pragma unroll
;     for (int n = 0; n < 4; ++n) gv[n] = MODS[(l * 3 + v) * 6144 + 2048 + nt * 128 + wc * 64 + n * 16 + fr];
; #pragma unroll
;     for (int m = 0; m < 8; ++m)
; #pragma unroll
;       for (int j = 0; j < 4; ++j) {
;         int row = row0 + wr * 128 + m * 16 + fq * 4 + j;
;         float* orow = O + (size_t)row * 1024 + nt * 128 + wc * 64 + fr;
; #pragma unroll
;         for (int n = 0; n < 4; ++n) unsafeAtomicAdd(orow + n * 16, gv[n] * acc[m][n][j]);
;       }
;   };
	v_add_u32_e32 v134, 0x32000, v142
	global_store_dword v134, v82, s[12:13]
	global_store_dword v134, v78, s[12:13] offset:64
	global_store_dword v134, v74, s[12:13] offset:128
	global_store_dword v134, v70, s[12:13] offset:192
	v_add_u32_e32 v135, 0x33000, v142
	global_store_dword v135, v83, s[12:13]
	global_store_dword v135, v79, s[12:13] offset:64
	global_store_dword v135, v75, s[12:13] offset:128
	global_store_dword v135, v71, s[12:13] offset:192
	v_add_u32_e32 v132, 0x40000, v142
	global_store_dword v132, v64, s[12:13]
	global_store_dword v132, v60, s[12:13] offset:64
	global_store_dword v132, v56, s[12:13] offset:128
	global_store_dword v132, v52, s[12:13] offset:192
	v_add_u32_e32 v133, 0x41000, v142
	global_store_dword v133, v65, s[12:13]
	global_store_dword v133, v61, s[12:13] offset:64
	global_store_dword v133, v57, s[12:13] offset:128
	global_store_dword v133, v53, s[12:13] offset:192
	v_add_u32_e32 v134, 0x42000, v142
	global_store_dword v134, v66, s[12:13]
	global_store_dword v134, v62, s[12:13] offset:64
	global_store_dword v134, v58, s[12:13] offset:128
	global_store_dword v134, v54, s[12:13] offset:192
	v_add_u32_e32 v135, 0x43000, v142
	global_store_dword v135, v67, s[12:13]
	global_store_dword v135, v63, s[12:13] offset:64
	global_store_dword v135, v59, s[12:13] offset:128
	global_store_dword v135, v55, s[12:13] offset:192
	v_add_u32_e32 v132, 0x50000, v142
	global_store_dword v132, v48, s[12:13]
	global_store_dword v132, v44, s[12:13] offset:64
	global_store_dword v132, v40, s[12:13] offset:128
	global_store_dword v132, v36, s[12:13] offset:192
	v_add_u32_e32 v133, 0x51000, v142
	global_store_dword v133, v49, s[12:13]
	global_store_dword v133, v45, s[12:13] offset:64
	global_store_dword v133, v41, s[12:13] offset:128
	global_store_dword v133, v37, s[12:13] offset:192
	v_add_u32_e32 v134, 0x52000, v142
	global_store_dword v134, v50, s[12:13]
	global_store_dword v134, v46, s[12:13] offset:64
	global_store_dword v134, v42, s[12:13] offset:128
	global_store_dword v134, v38, s[12:13] offset:192
	v_add_u32_e32 v135, 0x53000, v142
	global_store_dword v135, v51, s[12:13]
	global_store_dword v135, v47, s[12:13] offset:64
	global_store_dword v135, v43, s[12:13] offset:128
	global_store_dword v135, v39, s[12:13] offset:192
	v_add_u32_e32 v132, 0x60000, v142
	global_store_dword v132, v32, s[12:13]
	global_store_dword v132, v28, s[12:13] offset:64
	global_store_dword v132, v24, s[12:13] offset:128
	global_store_dword v132, v20, s[12:13] offset:192
	v_add_u32_e32 v133, 0x61000, v142
	global_store_dword v133, v33, s[12:13]
	global_store_dword v133, v29, s[12:13] offset:64
	global_store_dword v133, v25, s[12:13] offset:128
	global_store_dword v133, v21, s[12:13] offset:192
	v_add_u32_e32 v134, 0x62000, v142
	global_store_dword v134, v34, s[12:13]
	global_store_dword v134, v30, s[12:13] offset:64
	global_store_dword v134, v26, s[12:13] offset:128
	global_store_dword v134, v22, s[12:13] offset:192
	v_add_u32_e32 v135, 0x63000, v142
	global_store_dword v135, v35, s[12:13]
	global_store_dword v135, v31, s[12:13] offset:64
	global_store_dword v135, v27, s[12:13] offset:128
	global_store_dword v135, v23, s[12:13] offset:192
	v_add_u32_e32 v132, 0x70000, v142
	global_store_dword v132, v16, s[12:13]
	global_store_dword v132, v12, s[12:13] offset:64
	global_store_dword v132, v8, s[12:13] offset:128
	global_store_dword v132, v4, s[12:13] offset:192
	v_add_u32_e32 v133, 0x71000, v142
	global_store_dword v133, v17, s[12:13]
	global_store_dword v133, v13, s[12:13] offset:64
	global_store_dword v133, v9, s[12:13] offset:128
	global_store_dword v133, v5, s[12:13] offset:192
	v_add_u32_e32 v134, 0x72000, v142
	global_store_dword v134, v18, s[12:13]
	global_store_dword v134, v14, s[12:13] offset:64
	global_store_dword v134, v10, s[12:13] offset:128
	global_store_dword v134, v6, s[12:13] offset:192
	v_add_u32_e32 v135, 0x73000, v142
	global_store_dword v135, v19, s[12:13]
	global_store_dword v135, v15, s[12:13] offset:64
	global_store_dword v135, v11, s[12:13] offset:128
	global_store_dword v135, v7, s[12:13] offset:192
	s_branch .LBB0_1195

; __device__ __forceinline__ unsigned pack2(float a, float b) { return (unsigned)f2bf(a) | ((unsigned)f2bf(b) << 16); }
; __device__ __forceinline__ void norm_job(const Params& p, int l, int job, bool from_x) {
;     ...
;   for (int i = 0; i < 16; ++i) {
;     int row = rowbase0 + i;
;     int v = row < MLAT ? (row >> 13) : 2;
;     const float* mods = (const float*)(ws + OFF_MODS) + (l * 3 + v) * 6144;
;     float4 xv[4];
;     xv[0] = nx0; xv[1] = nx1; xv[2] = nx2; xv[3] = nx3;
;     if (i + 1 < 16) {
;       const float* sn = src0 + (size_t)(i + 1) * 1024;
;       nx0 = *(const float4*)&sn[lane * 4]; nx1 = *(const float4*)&sn[lane * 4 + 256];
;       nx2 = *(const float4*)&sn[lane * 4 + 512]; nx3 = *(const float4*)&sn[lane * 4 + 768];
;     }
;     float ss = 0.f;
; #pragma unroll
;     for (int q = 0; q < 4; ++q) {
;       ss += xv[q].x * xv[q].x + xv[q].y * xv[q].y + xv[q].z * xv[q].z + xv[q].w * xv[q].w;
;     }
;     ss = wave_sum(ss);
;     float rstd = rsqrtf(ss * (1.f / 1024.f) + EPSF);
;     if (from_x) {
;       float* dstr = (float*)(ws + OFF_XNEW) + (size_t)row * 1024;
; #pragma unroll
;       for (int q = 0; q < 4; ++q) *(float4*)&dstr[lane * 4 + 256 * q] = xv[q];
;     } else if (row < MLAT) {
;       float* dstr = p.out + (size_t)row * 1024;
; #pragma unroll
;       for (int q = 0; q < 4; ++q) *(float4*)&dstr[lane * 4 + 256 * q] = xv[q];
;     }
; #pragma unroll
;     for (int q = 0; q < 4; ++q) {
;       int col = lane * 4 + 256 * q;
;       float4 w = *(const float4*)&nw[col];
;       float4 sh = *(const float4*)&mods[col];
;       float4 sc = *(const float4*)&mods[1024 + col];
;       float o0 = xv[q].x * rstd * w.x * (1.f + sc.x) + sh.x;
;       float o1 = xv[q].y * rstd * w.y * (1.f + sc.y) + sh.y;
;       float o2 = xv[q].z * rstd * w.z * (1.f + sc.z) + sh.z;
;       float o3 = xv[q].w * rstd * w.w * (1.f + sc.w) + sh.w;
;       uint2 o; o.x = pack2(o0, o1); o.y = pack2(o2, o3);
;       *(uint2*)&HL[(size_t)row * 1024 + col] = o;
;     }
;   }
.LBB0_2023:
	v_lshl_add_u64 v[2:3], v[46:47], 0, s[8:9]
	v_add_co_u32_e32 v2, vcc, 0x2a197000, v2
	s_waitcnt vmcnt(0) lgkmcnt(0)
	v_mov_b32_e32 v58, v31
	v_addc_co_u32_e32 v3, vcc, 0, v3, vcc
	global_load_dwordx4 v[14:17], v[2:3], off offset:256
	global_load_dwordx4 v[10:13], v[2:3], off offset:1280
	global_load_dwordx4 v[6:9], v[2:3], off offset:2304
	s_nop 0
	global_load_dwordx4 v[2:5], v[2:3], off offset:3328
	v_mov_b32_e32 v59, v27
	v_mov_b32_e32 v50, v30
	v_mov_b32_e32 v51, v26
	v_pk_mul_f32 v[58:59], v[58:59], v[58:59]
	v_mov_b32_e32 v60, v23
	v_pk_fma_f32 v[50:51], v[50:51], v[50:51], v[58:59]
	v_mov_b32_e32 v58, v32
	v_mov_b32_e32 v59, v28
	v_pk_fma_f32 v[50:51], v[58:59], v[58:59], v[50:51]
	v_mov_b32_e32 v58, v33
	v_mov_b32_e32 v59, v29
	v_mov_b32_e32 v61, v19
	v_pk_fma_f32 v[50:51], v[58:59], v[58:59], v[50:51]
	v_mov_b32_e32 v58, v22
	v_mov_b32_e32 v59, v18
	v_pk_mul_f32 v[60:61], v[60:61], v[60:61]
	v_add_f32_e32 v0, v50, v51
	v_pk_fma_f32 v[58:59], v[58:59], v[58:59], v[60:61]
	v_mov_b32_e32 v60, v24
	v_mov_b32_e32 v61, v20
	v_pk_fma_f32 v[58:59], v[60:61], v[60:61], v[58:59]
	v_mov_b32_e32 v60, v25
	v_mov_b32_e32 v61, v21
	v_pk_fma_f32 v[58:59], v[60:61], v[60:61], v[58:59]
	v_cmp_gt_i32_e32 vcc, s91, v48
	v_add_f32_e32 v0, v0, v58
	v_add_f32_e32 v0, v0, v59
	ds_bpermute_b32 v50, v39, v0
	s_waitcnt lgkmcnt(0)
	v_add_f32_e32 v0, v0, v50
	ds_bpermute_b32 v50, v52, v0
	s_waitcnt lgkmcnt(0)
	v_add_f32_e32 v0, v0, v50
	ds_bpermute_b32 v50, v53, v0
	s_waitcnt lgkmcnt(0)
	v_add_f32_e32 v0, v0, v50
	ds_bpermute_b32 v50, v54, v0
	s_waitcnt lgkmcnt(0)
	v_add_f32_e32 v0, v0, v50
	ds_bpermute_b32 v50, v55, v0
	s_waitcnt lgkmcnt(0)
	v_add_f32_e32 v0, v0, v50
	ds_bpermute_b32 v57, v56, v0
	v_mov_b64_e32 v[50:51], v[48:49]
	s_and_saveexec_b64 s[10:11], vcc
	s_cbranch_execz .LBB0_2025
	v_ashrrev_i32_e32 v51, 31, v48
	v_mov_b32_e32 v50, v48
	v_lshlrev_b64 v[58:59], 12, v[50:51]
	v_lshl_add_u64 v[58:59], v[40:41], 0, v[58:59]
.LBB0_2025:
	s_or_b64 exec, exec, s[10:11]
	v_cndmask_b32_e32 v58, 2, v37, vcc
	v_add_u32_e32 v58, s12, v58
	s_movk_i32 s1, 0x1800
	v_mul_lo_u32 v62, v58, s1
	v_ashrrev_i32_e32 v63, 31, v62
	v_lshl_add_u64 v[70:71], v[62:63], 2, v[42:43]
	s_movk_i32 s1, 0x1000
	v_add_co_u32_e32 v72, vcc, s1, v70
	v_mov_b64_e32 v[58:59], v[186:187]
	v_mov_b64_e32 v[60:61], v[188:189]
	s_nop 0
	v_addc_co_u32_e32 v73, vcc, 0, v71, vcc
	v_mov_b64_e32 v[62:63], v[190:191]
	v_mov_b64_e32 v[64:65], v[192:193]
	v_mov_b64_e32 v[66:67], v[212:213]
	v_mov_b64_e32 v[68:69], v[214:215]
	s_waitcnt lgkmcnt(0)
	v_add_f32_e32 v0, v0, v57
	v_fmamk_f32 v0, v0, 0x3a800000, v197
	v_mov_b32_e32 v74, v30
	v_mul_f32_e32 v30, 0x4b800000, v0
	v_cmp_gt_f32_e32 vcc, s92, v0
	v_lshlrev_b64 v[50:51], 11, v[50:51]
	v_mov_b32_e32 v75, v32
	v_cndmask_b32_e32 v0, v0, v30, vcc
	v_rsq_f32_e32 v0, v0
	v_mov_b32_e32 v32, v31
	v_lshl_add_u64 v[30:31], v[44:45], 0, v[50:51]
	s_add_u32 s8, s8, 0x1000
	v_mul_f32_e32 v50, 0x45800000, v0
	v_cndmask_b32_e32 v0, v0, v50, vcc
	v_pk_mul_f32 v[50:51], v[74:75], v[0:1] op_sel_hi:[1,0]
	v_pk_mul_f32 v[32:33], v[32:33], v[0:1] op_sel_hi:[1,0]
	s_addc_u32 s9, s9, 0
	s_cmpk_eq_u32 s8, 0xf000
	v_lshl_add_u64 v[48:49], v[48:49], 0, 1
	s_waitcnt vmcnt(0)
	v_mov_b32_e32 v75, v60
	v_mov_b32_e32 v60, v59
	v_pk_mul_f32 v[32:33], v[32:33], v[60:61]
	v_mov_b32_e32 v74, v58
	v_mov_b32_e32 v61, v68
	v_mov_b32_e32 v68, v67
	v_mov_b32_e32 v58, v62
	v_mov_b32_e32 v59, v64
	v_mov_b32_e32 v64, v63
	v_mov_b32_e32 v60, v66
	v_pk_add_f32 v[62:63], v[68:69], 1.0 op_sel_hi:[1,0]
	v_pk_mul_f32 v[50:51], v[50:51], v[74:75]
	v_pk_add_f32 v[60:61], v[60:61], 1.0 op_sel_hi:[1,0]
	v_pk_fma_f32 v[32:33], v[32:33], v[62:63], v[64:65]
	v_pk_fma_f32 v[50:51], v[50:51], v[60:61], v[58:59]
	v_and_b32_sdwa v59, v33, v198 dst_sel:DWORD dst_unused:UNUSED_PAD src0_sel:WORD_1 src1_sel:DWORD
	v_and_b32_sdwa v60, v32, v198 dst_sel:DWORD dst_unused:UNUSED_PAD src0_sel:WORD_1 src1_sel:DWORD
	v_and_b32_sdwa v57, v51, v198 dst_sel:DWORD dst_unused:UNUSED_PAD src0_sel:WORD_1 src1_sel:DWORD
	v_and_b32_sdwa v58, v50, v198 dst_sel:DWORD dst_unused:UNUSED_PAD src0_sel:WORD_1 src1_sel:DWORD
	v_add3_u32 v33, v33, v59, s33
	v_add3_u32 v32, v32, v60, s33
	v_add3_u32 v50, v50, v58, s33
	v_add3_u32 v51, v51, v57, s33
	v_and_b32_e32 v33, 0xffff0000, v33
	v_and_b32_e32 v32, 0xffff0000, v32
	v_or_b32_sdwa v33, v33, v51 dst_sel:DWORD dst_unused:UNUSED_PAD src0_sel:DWORD src1_sel:WORD_1
	v_or_b32_sdwa v32, v32, v50 dst_sel:DWORD dst_unused:UNUSED_PAD src0_sel:DWORD src1_sel:WORD_1
	global_store_dwordx2 v[30:31], v[32:33], off
	v_mov_b64_e32 v[58:59], v[216:217]
	v_mov_b64_e32 v[60:61], v[218:219]
	v_mov_b64_e32 v[62:63], v[224:225]
	v_mov_b64_e32 v[64:65], v[226:227]
	v_mov_b64_e32 v[66:67], v[220:221]
	v_mov_b64_e32 v[68:69], v[222:223]
	v_mov_b32_e32 v32, v26
	v_mov_b32_e32 v33, v28
	v_mov_b32_e32 v28, v27
	v_pk_mul_f32 v[26:27], v[32:33], v[0:1] op_sel_hi:[1,0]
	v_pk_mul_f32 v[28:29], v[28:29], v[0:1] op_sel_hi:[1,0]
	v_mov_b32_e32 v32, v58
	v_mov_b32_e32 v33, v60
	s_waitcnt lgkmcnt(0)
; __device__ __forceinline__ unsigned pack2(float a, float b) { return (unsigned)f2bf(a) | ((unsigned)f2bf(b) << 16); }
; __device__ __forceinline__ void norm_job(const Params& p, int l, int job, bool from_x) {
;     ...
;   for (int i = 0; i < 16; ++i) {
;     int row = rowbase0 + i;
;     int v = row < MLAT ? (row >> 13) : 2;
;     const float* mods = (const float*)(ws + OFF_MODS) + (l * 3 + v) * 6144;
;     float4 xv[4];
;     xv[0] = nx0; xv[1] = nx1; xv[2] = nx2; xv[3] = nx3;
;     if (i + 1 < 16) {
;       const float* sn = src0 + (size_t)(i + 1) * 1024;
;       nx0 = *(const float4*)&sn[lane * 4]; nx1 = *(const float4*)&sn[lane * 4 + 256];
;       nx2 = *(const float4*)&sn[lane * 4 + 512]; nx3 = *(const float4*)&sn[lane * 4 + 768];
;     }
;     float ss = 0.f;
; #pragma unroll
;     for (int q = 0; q < 4; ++q) {
;       ss += xv[q].x * xv[q].x + xv[q].y * xv[q].y + xv[q].z * xv[q].z + xv[q].w * xv[q].w;
;     }
;     ss = wave_sum(ss);
;     float rstd = rsqrtf(ss * (1.f / 1024.f) + EPSF);
;     if (from_x) {
;       float* dstr = (float*)(ws + OFF_XNEW) + (size_t)row * 1024;
; #pragma unroll
;       for (int q = 0; q < 4; ++q) *(float4*)&dstr[lane * 4 + 256 * q] = xv[q];
;     } else if (row < MLAT) {
;       float* dstr = p.out + (size_t)row * 1024;
; #pragma unroll
;       for (int q = 0; q < 4; ++q) *(float4*)&dstr[lane * 4 + 256 * q] = xv[q];
;     }
; #pragma unroll
;     for (int q = 0; q < 4; ++q) {
;       int col = lane * 4 + 256 * q;
;       float4 w = *(const float4*)&nw[col];
;       float4 sh = *(const float4*)&mods[col];
;       float4 sc = *(const float4*)&mods[1024 + col];
;       float o0 = xv[q].x * rstd * w.x * (1.f + sc.x) + sh.x;
;       float o1 = xv[q].y * rstd * w.y * (1.f + sc.y) + sh.y;
;       float o2 = xv[q].z * rstd * w.z * (1.f + sc.z) + sh.z;
;       float o3 = xv[q].w * rstd * w.w * (1.f + sc.w) + sh.w;
;       uint2 o; o.x = pack2(o0, o1); o.y = pack2(o2, o3);
;       *(uint2*)&HL[(size_t)row * 1024 + col] = o;
;     }
;   }
	v_mov_b32_e32 v50, v62
	v_mov_b32_e32 v51, v64
	v_mov_b32_e32 v60, v59
	v_mov_b32_e32 v64, v63
	v_mov_b32_e32 v75, v68
	v_mov_b32_e32 v68, v67
	v_pk_mul_f32 v[26:27], v[26:27], v[32:33]
	v_pk_add_f32 v[32:33], v[50:51], 1.0 op_sel_hi:[1,0]
	v_pk_mul_f32 v[28:29], v[28:29], v[60:61]
	v_pk_add_f32 v[50:51], v[64:65], 1.0 op_sel_hi:[1,0]
	v_mov_b32_e32 v74, v66
	v_pk_fma_f32 v[28:29], v[28:29], v[50:51], v[68:69]
	v_pk_fma_f32 v[26:27], v[26:27], v[32:33], v[74:75]
	v_and_b32_sdwa v50, v29, v198 dst_sel:DWORD dst_unused:UNUSED_PAD src0_sel:WORD_1 src1_sel:DWORD
	v_and_b32_sdwa v51, v28, v198 dst_sel:DWORD dst_unused:UNUSED_PAD src0_sel:WORD_1 src1_sel:DWORD
	v_and_b32_sdwa v32, v27, v198 dst_sel:DWORD dst_unused:UNUSED_PAD src0_sel:WORD_1 src1_sel:DWORD
	v_and_b32_sdwa v33, v26, v198 dst_sel:DWORD dst_unused:UNUSED_PAD src0_sel:WORD_1 src1_sel:DWORD
	v_add3_u32 v29, v29, v50, s33
	v_add3_u32 v28, v28, v51, s33
	v_add3_u32 v26, v26, v33, s33
	v_add3_u32 v27, v27, v32, s33
	v_and_b32_e32 v29, 0xffff0000, v29
	v_and_b32_e32 v28, 0xffff0000, v28
	v_or_b32_sdwa v27, v29, v27 dst_sel:DWORD dst_unused:UNUSED_PAD src0_sel:DWORD src1_sel:WORD_1
	v_or_b32_sdwa v26, v28, v26 dst_sel:DWORD dst_unused:UNUSED_PAD src0_sel:DWORD src1_sel:WORD_1
	global_store_dwordx2 v[30:31], v[26:27], off offset:512
	v_mov_b64_e32 v[26:27], v[228:229]
	v_mov_b64_e32 v[28:29], v[230:231]
	s_nop 0
	v_mov_b64_e32 v[58:59], v[240:241]
	v_mov_b64_e32 v[60:61], v[242:243]
	v_mov_b64_e32 v[62:63], v[232:233]
	v_mov_b64_e32 v[64:65], v[234:235]
	v_mov_b32_e32 v32, v22
	v_mov_b32_e32 v33, v24
	v_mov_b32_e32 v24, v23
	v_pk_mul_f32 v[22:23], v[32:33], v[0:1] op_sel_hi:[1,0]
	v_pk_mul_f32 v[24:25], v[24:25], v[0:1] op_sel_hi:[1,0]
	v_mov_b32_e32 v33, v28
	s_waitcnt lgkmcnt(0)
	v_mov_b32_e32 v51, v60
	v_mov_b32_e32 v28, v27
	v_mov_b32_e32 v60, v59
	v_mov_b32_e32 v32, v26
	v_mov_b32_e32 v50, v58
	v_mov_b32_e32 v67, v64
	v_mov_b32_e32 v64, v63
	v_pk_mul_f32 v[24:25], v[24:25], v[28:29]
	v_pk_add_f32 v[28:29], v[60:61], 1.0 op_sel_hi:[1,0]
	v_mov_b32_e32 v66, v62
	v_pk_mul_f32 v[22:23], v[22:23], v[32:33]
	v_pk_add_f32 v[26:27], v[50:51], 1.0 op_sel_hi:[1,0]
	v_pk_fma_f32 v[24:25], v[24:25], v[28:29], v[64:65]
	v_pk_fma_f32 v[22:23], v[22:23], v[26:27], v[66:67]
	v_and_b32_sdwa v28, v25, v198 dst_sel:DWORD dst_unused:UNUSED_PAD src0_sel:WORD_1 src1_sel:DWORD
	v_and_b32_sdwa v29, v24, v198 dst_sel:DWORD dst_unused:UNUSED_PAD src0_sel:WORD_1 src1_sel:DWORD
	v_and_b32_sdwa v26, v23, v198 dst_sel:DWORD dst_unused:UNUSED_PAD src0_sel:WORD_1 src1_sel:DWORD
	v_and_b32_sdwa v27, v22, v198 dst_sel:DWORD dst_unused:UNUSED_PAD src0_sel:WORD_1 src1_sel:DWORD
	v_add3_u32 v25, v25, v28, s33
	v_add3_u32 v24, v24, v29, s33
	v_add3_u32 v22, v22, v27, s33
	v_add3_u32 v23, v23, v26, s33
	v_and_b32_e32 v25, 0xffff0000, v25
	v_and_b32_e32 v24, 0xffff0000, v24
	v_or_b32_sdwa v23, v25, v23 dst_sel:DWORD dst_unused:UNUSED_PAD src0_sel:DWORD src1_sel:WORD_1
	v_or_b32_sdwa v22, v24, v22 dst_sel:DWORD dst_unused:UNUSED_PAD src0_sel:DWORD src1_sel:WORD_1
	global_store_dwordx2 v[30:31], v[22:23], off offset:1024
	v_mov_b64_e32 v[22:23], v[244:245]
	v_mov_b64_e32 v[24:25], v[246:247]
	s_nop 0
	v_mov_b64_e32 v[26:27], v[252:253]
	v_mov_b64_e32 v[28:29], v[254:255]
	v_mov_b64_e32 v[58:59], v[248:249]
	v_mov_b64_e32 v[60:61], v[250:251]
	v_mov_b32_e32 v32, v18
	v_mov_b32_e32 v33, v20
	v_mov_b32_e32 v20, v19
	v_pk_mul_f32 v[18:19], v[32:33], v[0:1] op_sel_hi:[1,0]
	v_pk_mul_f32 v[20:21], v[20:21], v[0:1] op_sel_hi:[1,0]
	v_mov_b32_e32 v32, v22
	v_mov_b32_e32 v33, v24
	s_waitcnt lgkmcnt(0)
	v_mov_b32_e32 v50, v26
	v_mov_b32_e32 v51, v28
	v_mov_b32_e32 v24, v23
	v_mov_b32_e32 v28, v27
	v_mov_b32_e32 v62, v58
	v_mov_b32_e32 v63, v60
	v_mov_b32_e32 v60, v59
	v_pk_mul_f32 v[18:19], v[18:19], v[32:33]
	v_pk_add_f32 v[22:23], v[50:51], 1.0 op_sel_hi:[1,0]
	v_pk_mul_f32 v[20:21], v[20:21], v[24:25]
	v_pk_add_f32 v[24:25], v[28:29], 1.0 op_sel_hi:[1,0]
	v_pk_fma_f32 v[18:19], v[18:19], v[22:23], v[62:63]
	v_pk_fma_f32 v[20:21], v[20:21], v[24:25], v[60:61]
	v_and_b32_sdwa v0, v19, v198 dst_sel:DWORD dst_unused:UNUSED_PAD src0_sel:WORD_1 src1_sel:DWORD
	v_and_b32_sdwa v23, v21, v198 dst_sel:DWORD dst_unused:UNUSED_PAD src0_sel:WORD_1 src1_sel:DWORD
	v_and_b32_sdwa v24, v20, v198 dst_sel:DWORD dst_unused:UNUSED_PAD src0_sel:WORD_1 src1_sel:DWORD
	v_and_b32_sdwa v22, v18, v198 dst_sel:DWORD dst_unused:UNUSED_PAD src0_sel:WORD_1 src1_sel:DWORD
	v_add3_u32 v0, v19, v0, s33
	v_add3_u32 v19, v21, v23, s33
	v_add3_u32 v20, v20, v24, s33
	v_add3_u32 v18, v18, v22, s33
	v_and_b32_e32 v19, 0xffff0000, v19
	v_and_b32_e32 v20, 0xffff0000, v20
	v_or_b32_sdwa v19, v19, v0 dst_sel:DWORD dst_unused:UNUSED_PAD src0_sel:DWORD src1_sel:WORD_1
	v_or_b32_sdwa v18, v20, v18 dst_sel:DWORD dst_unused:UNUSED_PAD src0_sel:DWORD src1_sel:WORD_1
	global_store_dwordx2 v[30:31], v[18:19], off offset:1536
	s_cbranch_scc1 .LBB0_2027
	v_mov_b64_e32 v[32:33], v[16:17]
	v_mov_b64_e32 v[28:29], v[12:13]
	v_mov_b64_e32 v[24:25], v[8:9]
	v_mov_b64_e32 v[20:21], v[4:5]
	v_mov_b64_e32 v[30:31], v[14:15]
	v_mov_b64_e32 v[26:27], v[10:11]
	v_mov_b64_e32 v[22:23], v[6:7]
	v_mov_b64_e32 v[18:19], v[2:3]
	s_branch .LBB0_2023
.LBB0_2027:
	v_mul_f32_e32 v0, v15, v15
	v_mul_f32_e32 v18, v11, v11
	v_fmac_f32_e32 v0, v14, v14
	v_fmac_f32_e32 v18, v10, v10
	v_fmac_f32_e32 v0, v16, v16
	v_fmac_f32_e32 v18, v12, v12
	v_fmac_f32_e32 v0, v17, v17
	v_fmac_f32_e32 v18, v13, v13
	v_add_f32_e32 v0, v0, v18
	v_mul_f32_e32 v18, v7, v7
	v_fmac_f32_e32 v18, v6, v6
	v_fmac_f32_e32 v18, v8, v8
	v_fmac_f32_e32 v18, v9, v9
	v_add_f32_e32 v0, v0, v18
	v_mul_f32_e32 v18, v3, v3
	v_fmac_f32_e32 v18, v2, v2
	v_fmac_f32_e32 v18, v4, v4
	v_fmac_f32_e32 v18, v5, v5
	v_add_f32_e32 v0, v0, v18
	ds_bpermute_b32 v18, v39, v0
	s_movk_i32 s1, 0x3fff
	s_waitcnt lgkmcnt(0)
	v_add_f32_e32 v0, v0, v18
	ds_bpermute_b32 v18, v52, v0
	s_waitcnt lgkmcnt(0)
	v_add_f32_e32 v0, v0, v18
	ds_bpermute_b32 v18, v53, v0
	s_waitcnt lgkmcnt(0)
	v_add_f32_e32 v0, v0, v18
	ds_bpermute_b32 v18, v54, v0
	s_waitcnt lgkmcnt(0)
	v_add_f32_e32 v0, v0, v18
	ds_bpermute_b32 v18, v55, v0
	s_waitcnt lgkmcnt(0)
	v_add_f32_e32 v20, v0, v18
	ds_bpermute_b32 v21, v56, v20
	v_or_b32_e32 v18, 15, v38
	v_cmp_lt_i32_e32 vcc, s1, v18
	s_and_saveexec_b64 s[8:9], vcc
	s_xor_b64 s[8:9], exec, s[8:9]
	v_mov_b32_e32 v19, v1
	s_or_saveexec_b64 s[8:9], s[8:9]
	v_mov_b32_e32 v22, 2
	v_lshlrev_b32_e32 v0, 2, v36
	s_xor_b64 exec, exec, s[8:9]
	s_cbranch_execz .LBB0_2021
	v_ashrrev_i32_e32 v19, 31, v18
	v_lshlrev_b64 v[22:23], 12, v[18:19]
	v_lshl_add_u64 v[22:23], s[56:57], 0, v[22:23]
	v_mov_b32_e32 v24, v0
	v_mov_b32_e32 v25, v1
	v_lshl_add_u64 v[22:23], v[22:23], 0, v[24:25]
	v_mov_b32_e32 v22, v37
	s_branch .LBB0_2021
